# v076 stack + row sums in attention epilogues and SSD combine: xor-1/2/4/8 butterfly steps via DPP adds instead of ds_swizzle round trips
# speedup vs baseline: 1.0039x; 1.0039x over previous
.LBB0_705:
	s_andn2_b64 vcc, exec, s[6:7]
	s_mov_b64 s[6:7], 0
	s_cbranch_vccnz .LBB0_711
	s_nop 2
	v_exp_f32_e32 v146, v146
	v_exp_f32_e32 v207, v147
	v_exp_f32_e32 v147, v148
	v_exp_f32_e32 v208, v149
	v_exp_f32_e32 v209, v150
	v_add_f32_e32 v148, v207, v146
	v_exp_f32_e32 v210, v151
	v_add_f32_e32 v148, v147, v148
	v_exp_f32_e32 v151, v152
	v_add_f32_e32 v148, v208, v148
	v_exp_f32_e32 v211, v153
	v_add_f32_e32 v148, v209, v148
	v_add_f32_e32 v148, v210, v148
	v_add_f32_e32 v148, v151, v148
	v_add_f32_e32 v150, v211, v148
	v_exp_f32_e32 v148, v154
	v_exp_f32_e32 v152, v155
	v_exp_f32_e32 v149, v156
	v_exp_f32_e32 v153, v157
	v_add_f32_e32 v150, v148, v150
	v_exp_f32_e32 v154, v158
	v_add_f32_e32 v150, v152, v150
	v_exp_f32_e32 v158, v159
	v_add_f32_e32 v150, v149, v150
	v_exp_f32_e32 v155, v160
	v_add_f32_e32 v150, v153, v150
	v_exp_f32_e32 v159, v161
	v_add_f32_e32 v150, v154, v150
	v_add_f32_e32 v150, v158, v150
	v_add_f32_e32 v150, v155, v150
	v_add_f32_e32 v160, v159, v150
	v_exp_f32_e32 v150, v130
	v_exp_f32_e32 v156, v131
	v_exp_f32_e32 v131, v132
	v_exp_f32_e32 v157, v133
	v_add_f32_e32 v130, v150, v160
	v_exp_f32_e32 v134, v134
	v_add_f32_e32 v130, v156, v130
	v_exp_f32_e32 v160, v135
	v_add_f32_e32 v130, v131, v130
	v_exp_f32_e32 v135, v136
	v_add_f32_e32 v130, v157, v130
	v_exp_f32_e32 v161, v137
	v_add_f32_e32 v130, v134, v130
	v_exp_f32_e32 v132, v138
	v_add_f32_e32 v130, v160, v130
	v_exp_f32_e32 v136, v139
	v_add_f32_e32 v130, v135, v130
	v_exp_f32_e32 v133, v140
	v_add_f32_e32 v130, v161, v130
	v_exp_f32_e32 v137, v141
	v_add_f32_e32 v130, v132, v130
	v_exp_f32_e32 v138, v142
	v_add_f32_e32 v130, v136, v130
	v_exp_f32_e32 v140, v143
	v_add_f32_e32 v130, v133, v130
	v_exp_f32_e32 v139, v144
	v_add_f32_e32 v130, v137, v130
	v_exp_f32_e32 v141, v145
	v_add_f32_e32 v130, v138, v130
	v_add_f32_e32 v130, v140, v130
	v_add_f32_e32 v130, v139, v130
	v_add_f32_e32 v130, v141, v130
	v_mov_b32_e32 v142, v130
	s_nop 1
	v_permlane32_swap_b32_e32 v130, v142
	v_add_f32_e32 v130, v130, v142
	s_mov_b32 s10, 0x71800000
	v_cmp_ge_f32_e32 vcc, s10, v130
	s_cmp_lg_u64 vcc, exec
	s_mov_b64 s[10:11], 0
	s_cbranch_scc1 .LBB0_712
	s_mov_b64 s[10:11], -1
	v_mov_b32_e32 v204, v130
	v_cvt_pk_bf16_f32 v162, v146, v207
	v_cvt_pk_bf16_f32 v163, v147, v208
	v_cvt_pk_bf16_f32 v164, v209, v210
	v_cvt_pk_bf16_f32 v165, v151, v211
	v_cvt_pk_bf16_f32 v166, v148, v152
	v_cvt_pk_bf16_f32 v167, v149, v153
	v_cvt_pk_bf16_f32 v168, v154, v158
	v_cvt_pk_bf16_f32 v169, v155, v159
	v_cvt_pk_bf16_f32 v170, v150, v156
	v_cvt_pk_bf16_f32 v171, v131, v157
	v_cvt_pk_bf16_f32 v172, v134, v160
	v_cvt_pk_bf16_f32 v173, v135, v161
	v_cvt_pk_bf16_f32 v174, v132, v136
	v_cvt_pk_bf16_f32 v175, v133, v137
	v_cvt_pk_bf16_f32 v176, v138, v140
	v_cvt_pk_bf16_f32 v177, v139, v141
	s_branch .LBB0_712

.LBB0_716:
	s_andn2_b64 vcc, exec, s[6:7]
	s_mov_b64 s[6:7], 0
	s_cbranch_vccnz .LBB0_719
	s_nop 2
	v_exp_f32_e32 v146, v146
	v_exp_f32_e32 v206, v147
	v_exp_f32_e32 v147, v148
	v_exp_f32_e32 v207, v149
	v_exp_f32_e32 v208, v150
	v_add_f32_e32 v148, v206, v146
	v_exp_f32_e32 v209, v151
	v_add_f32_e32 v148, v147, v148
	v_exp_f32_e32 v151, v152
	v_add_f32_e32 v148, v207, v148
	v_exp_f32_e32 v210, v153
	v_add_f32_e32 v148, v208, v148
	v_add_f32_e32 v148, v209, v148
	v_add_f32_e32 v148, v151, v148
	v_add_f32_e32 v150, v210, v148
	v_exp_f32_e32 v148, v154
	v_exp_f32_e32 v152, v155
	v_exp_f32_e32 v149, v156
	v_exp_f32_e32 v153, v157
	v_add_f32_e32 v150, v148, v150
	v_exp_f32_e32 v154, v158
	v_add_f32_e32 v150, v152, v150
	v_exp_f32_e32 v158, v159
	v_add_f32_e32 v150, v149, v150
	v_exp_f32_e32 v155, v160
	v_add_f32_e32 v150, v153, v150
	v_exp_f32_e32 v159, v161
	v_add_f32_e32 v150, v154, v150
	v_add_f32_e32 v150, v158, v150
	v_add_f32_e32 v150, v155, v150
	v_add_f32_e32 v160, v159, v150
	v_exp_f32_e32 v150, v130
	v_exp_f32_e32 v156, v131
	v_exp_f32_e32 v131, v132
	v_exp_f32_e32 v157, v133
	v_add_f32_e32 v130, v150, v160
	v_exp_f32_e32 v134, v134
	v_add_f32_e32 v130, v156, v130
	v_exp_f32_e32 v160, v135
	v_add_f32_e32 v130, v131, v130
	v_exp_f32_e32 v135, v136
	v_add_f32_e32 v130, v157, v130
	v_exp_f32_e32 v161, v137
	v_add_f32_e32 v130, v134, v130
	v_exp_f32_e32 v132, v138
	v_add_f32_e32 v130, v160, v130
	v_exp_f32_e32 v136, v139
	v_add_f32_e32 v130, v135, v130
	v_exp_f32_e32 v133, v140
	v_add_f32_e32 v130, v161, v130
	v_exp_f32_e32 v137, v141
	v_add_f32_e32 v130, v132, v130
	v_exp_f32_e32 v138, v142
	v_add_f32_e32 v130, v136, v130
	v_exp_f32_e32 v140, v143
	v_add_f32_e32 v130, v133, v130
	v_exp_f32_e32 v139, v144
	v_add_f32_e32 v130, v137, v130
	v_exp_f32_e32 v141, v145
	v_add_f32_e32 v130, v138, v130
	v_add_f32_e32 v130, v140, v130
	v_add_f32_e32 v130, v139, v130
	v_add_f32_e32 v130, v141, v130
	v_mov_b32_e32 v142, v130
	s_nop 1
	v_permlane32_swap_b32_e32 v130, v142
	v_add_f32_e32 v130, v130, v142
	s_mov_b32 s6, 0x71800000
	v_cmp_ge_f32_e32 vcc, s6, v130
	s_cmp_lg_u64 vcc, exec
	s_mov_b64 s[6:7], 0
	s_cbranch_scc1 .LBB0_719
	s_mov_b64 s[6:7], -1
	v_mov_b32_e32 v205, v130
	v_cvt_pk_bf16_f32 v178, v146, v206
	v_cvt_pk_bf16_f32 v179, v147, v207
	v_cvt_pk_bf16_f32 v180, v208, v209
	v_cvt_pk_bf16_f32 v181, v151, v210
	v_cvt_pk_bf16_f32 v182, v148, v152
	v_cvt_pk_bf16_f32 v183, v149, v153
	v_cvt_pk_bf16_f32 v184, v154, v158
	v_cvt_pk_bf16_f32 v185, v155, v159
	v_cvt_pk_bf16_f32 v186, v150, v156
	v_cvt_pk_bf16_f32 v187, v131, v157
	v_cvt_pk_bf16_f32 v188, v134, v160
	v_cvt_pk_bf16_f32 v189, v135, v161
	v_cvt_pk_bf16_f32 v190, v132, v136
	v_cvt_pk_bf16_f32 v191, v133, v137
	v_cvt_pk_bf16_f32 v192, v138, v140
	v_cvt_pk_bf16_f32 v193, v139, v141

.LBB0_741:
	v_mbcnt_lo_u32_b32 v0, -1, 0
	v_mbcnt_hi_u32_b32 v0, -1, v0
	s_nop 0
	v_cmp_gt_u32_e32 vcc, 32, v0
	s_and_saveexec_b64 s[4:5], vcc
	v_lshl_add_u32 v130, v0, 2, s14
	ds_write2_b32 v130, v202, v203 offset0:64 offset1:96
	s_or_b64 exec, exec, s[4:5]
	v_ashrrev_i32_e32 v134, 5, v0
	s_waitcnt lgkmcnt(0)
	v_lshl_add_u32 v139, v134, 4, s14
	ds_read_b128 v[140:143], v139 offset:256
	ds_read_b128 v[130:133], v139 offset:288
	ds_read_b128 v[144:147], v139 offset:384
	v_readlane_b32 s2, v255, 35
	v_and_b32_e32 v0, 31, v0
	s_waitcnt lgkmcnt(2)
	v_rcp_f32_e32 v140, v140
	s_waitcnt lgkmcnt(0)
	v_rcp_f32_e32 v135, v144
	s_nop 0
	v_mul_f32_e32 v144, s2, v135
	v_mul_f32_e32 v2, v2, v144
	v_fma_f32 v137, v114, v140, -v2
	v_mul_f32_e32 v2, v66, v144
	v_fma_f32 v136, v98, v140, -v2
	v_mul_f32_e32 v2, v34, v144
	v_fma_f32 v135, v82, v140, -v2
	v_mul_f32_e32 v2, v18, v144
	v_rcp_f32_e32 v18, v145
	v_fma_f32 v114, v50, v140, -v2
	v_rcp_f32_e32 v2, v141
	v_mul_f32_e32 v138, v136, v136
	v_mul_f32_e32 v18, s2, v18
	v_mul_f32_e32 v3, v3, v18
	v_fma_f32 v98, v115, v2, -v3
	v_mul_f32_e32 v3, v67, v18
	v_fma_f32 v82, v99, v2, -v3
	v_mul_f32_e32 v3, v35, v18
	v_fma_f32 v67, v83, v2, -v3
	v_mul_f32_e32 v3, v19, v18
	v_fma_f32 v66, v51, v2, -v3
	v_rcp_f32_e32 v3, v146
	v_rcp_f32_e32 v2, v142
	v_fmac_f32_e32 v138, v137, v137
	v_fmac_f32_e32 v138, v135, v135
	v_mul_f32_e32 v3, s2, v3
	v_mul_f32_e32 v4, v4, v3
	v_fma_f32 v51, v116, v2, -v4
	v_mul_f32_e32 v4, v68, v3
	v_fma_f32 v50, v100, v2, -v4
	v_mul_f32_e32 v4, v36, v3
	v_mul_f32_e32 v3, v20, v3
	v_fma_f32 v35, v52, v2, -v3
	v_rcp_f32_e32 v3, v147
	v_fma_f32 v36, v84, v2, -v4
	v_rcp_f32_e32 v2, v143
	v_fmac_f32_e32 v138, v114, v114
	v_mul_f32_e32 v3, s2, v3
	v_mul_f32_e32 v4, v5, v3
	v_fma_f32 v34, v117, v2, -v4
	v_mul_f32_e32 v4, v69, v3
	v_fma_f32 v20, v101, v2, -v4
	v_mul_f32_e32 v4, v37, v3
	v_mul_f32_e32 v3, v21, v3
	v_fma_f32 v19, v85, v2, -v4
	v_fma_f32 v18, v53, v2, -v3
	ds_read_b128 v[2:5], v139 offset:416
	v_rcp_f32_e32 v21, v130
	v_mul_f32_e32 v115, v82, v82
	v_fmac_f32_e32 v115, v98, v98
	v_fmac_f32_e32 v115, v67, v67
	s_waitcnt lgkmcnt(0)
	v_rcp_f32_e32 v2, v2
	v_rcp_f32_e32 v3, v3
	v_fmac_f32_e32 v115, v66, v66
	v_mul_f32_e32 v99, v50, v50
	v_mul_f32_e32 v2, s2, v2
	v_mul_f32_e32 v6, v6, v2
	v_fma_f32 v52, v118, v21, -v6
	v_mul_f32_e32 v6, v70, v2
	v_fma_f32 v37, v102, v21, -v6
	v_mul_f32_e32 v6, v38, v2
	v_mul_f32_e32 v2, v22, v2
	v_fma_f32 v38, v86, v21, -v6
	v_fma_f32 v21, v54, v21, -v2
	v_rcp_f32_e32 v2, v131
	v_mul_f32_e32 v3, s2, v3
	v_mul_f32_e32 v6, v7, v3
	v_fmac_f32_e32 v99, v51, v51
	v_fma_f32 v54, v119, v2, -v6
	v_mul_f32_e32 v6, v71, v3
	v_fma_f32 v53, v103, v2, -v6
	v_mul_f32_e32 v6, v39, v3
	v_mul_f32_e32 v3, v23, v3
	v_fma_f32 v22, v55, v2, -v3
	v_rcp_f32_e32 v3, v4
	v_fma_f32 v39, v87, v2, -v6
	v_rcp_f32_e32 v2, v132
	v_fmac_f32_e32 v99, v36, v36
	v_mul_f32_e32 v3, s2, v3
	v_mul_f32_e32 v4, v8, v3
	v_fma_f32 v69, v120, v2, -v4
	v_mul_f32_e32 v4, v72, v3
	v_fma_f32 v55, v104, v2, -v4
	v_mul_f32_e32 v4, v40, v3
	v_mul_f32_e32 v3, v24, v3
	v_fma_f32 v40, v56, v2, -v3
	v_rcp_f32_e32 v3, v5
	v_fma_f32 v68, v88, v2, -v4
	v_rcp_f32_e32 v2, v133
	v_fmac_f32_e32 v99, v35, v35
	v_mul_f32_e32 v3, s2, v3
	v_mul_f32_e32 v4, v9, v3
	v_fma_f32 v72, v121, v2, -v4
	v_mul_f32_e32 v4, v73, v3
	v_fma_f32 v70, v105, v2, -v4
	v_mul_f32_e32 v4, v41, v3
	v_mul_f32_e32 v3, v25, v3
	v_fma_f32 v71, v89, v2, -v4
	v_fma_f32 v56, v57, v2, -v3
	ds_read_b128 v[2:5], v139 offset:320
	ds_read_b128 v[6:9], v139 offset:448
	v_mul_f32_e32 v84, v20, v20
	v_fmac_f32_e32 v84, v34, v34
	v_fmac_f32_e32 v84, v19, v19
	s_waitcnt lgkmcnt(1)
	v_rcp_f32_e32 v2, v2
	s_waitcnt lgkmcnt(0)
	v_rcp_f32_e32 v6, v6
	v_fmac_f32_e32 v84, v18, v18
	v_mul_f32_e32 v101, v37, v37
	v_fmac_f32_e32 v101, v52, v52
	v_mul_f32_e32 v6, s2, v6
	v_mul_f32_e32 v10, v10, v6
	v_fma_f32 v83, v122, v2, -v10
	v_mul_f32_e32 v10, v74, v6
	v_fma_f32 v74, v106, v2, -v10
	v_mul_f32_e32 v10, v42, v6
	v_mul_f32_e32 v6, v26, v6
	v_fma_f32 v73, v90, v2, -v10
	v_fma_f32 v58, v58, v2, -v6
	v_rcp_f32_e32 v2, v3
	v_rcp_f32_e32 v3, v7
	v_fmac_f32_e32 v101, v38, v38
	v_fmac_f32_e32 v101, v21, v21
	v_mul_f32_e32 v100, v53, v53
	v_mul_f32_e32 v3, s2, v3
	v_mul_f32_e32 v6, v11, v3
	v_fma_f32 v57, v123, v2, -v6
	v_mul_f32_e32 v6, v75, v3
	v_fma_f32 v42, v107, v2, -v6
	v_mul_f32_e32 v6, v43, v3
	v_mul_f32_e32 v3, v27, v3
	v_fma_f32 v27, v59, v2, -v3
	v_rcp_f32_e32 v3, v8
	v_fma_f32 v41, v91, v2, -v6
	v_rcp_f32_e32 v2, v4
	v_fmac_f32_e32 v100, v54, v54
	v_mul_f32_e32 v3, s2, v3
	v_mul_f32_e32 v4, v12, v3
	v_fma_f32 v26, v124, v2, -v4
	v_mul_f32_e32 v4, v76, v3
	v_fma_f32 v25, v108, v2, -v4
	v_mul_f32_e32 v4, v44, v3
	v_mul_f32_e32 v3, v28, v3
	v_fma_f32 v23, v60, v2, -v3
	v_rcp_f32_e32 v3, v9
	v_fma_f32 v24, v92, v2, -v4
	v_rcp_f32_e32 v2, v5
	ds_read_b128 v[6:9], v139 offset:480
	v_mul_f32_e32 v3, s2, v3
	v_mul_f32_e32 v4, v13, v3
	v_fma_f32 v13, v125, v2, -v4
	v_mul_f32_e32 v4, v77, v3
	v_fma_f32 v12, v109, v2, -v4
	v_mul_f32_e32 v4, v45, v3
	v_mul_f32_e32 v3, v29, v3
	v_fma_f32 v11, v93, v2, -v4
	v_fma_f32 v10, v61, v2, -v3
	ds_read_b128 v[2:5], v139 offset:352
	s_waitcnt lgkmcnt(1)
	v_rcp_f32_e32 v7, v7
	v_fmac_f32_e32 v100, v39, v39
	v_fmac_f32_e32 v100, v22, v22
	v_mul_f32_e32 v87, v55, v55
	s_waitcnt lgkmcnt(0)
	v_rcp_f32_e32 v43, v2
	v_rcp_f32_e32 v2, v6
	v_rcp_f32_e32 v3, v3
	v_mul_f32_e32 v7, s2, v7
	v_mul_f32_e32 v15, v15, v7
	v_mul_f32_e32 v6, s2, v2
	v_mul_f32_e32 v2, v14, v6
	v_fma_f32 v29, v126, v43, -v2
	v_mul_f32_e32 v2, v78, v6
	v_mul_f32_e32 v28, v46, v6
	v_mul_f32_e32 v6, v30, v6
	v_fma_f32 v14, v110, v43, -v2
	v_fma_f32 v28, v94, v43, -v28
	v_fma_f32 v6, v62, v43, -v6
	v_fma_f32 v43, v127, v3, -v15
	v_mul_f32_e32 v15, v79, v7
	v_mul_f32_e32 v30, v47, v7
	v_mul_f32_e32 v7, v31, v7
	v_fma_f32 v15, v111, v3, -v15
	v_fma_f32 v30, v95, v3, -v30
	v_fma_f32 v7, v63, v3, -v7
	v_rcp_f32_e32 v3, v4
	v_rcp_f32_e32 v4, v8
	v_fmac_f32_e32 v87, v69, v69
	v_fmac_f32_e32 v87, v68, v68
	v_fmac_f32_e32 v87, v40, v40
	v_mul_f32_e32 v4, s2, v4
	v_mul_f32_e32 v8, v16, v4
	v_fma_f32 v31, v128, v3, -v8
	v_mul_f32_e32 v8, v80, v4
	v_mul_f32_e32 v16, v48, v4
	v_mul_f32_e32 v4, v32, v4
	v_fma_f32 v8, v112, v3, -v8
	v_fma_f32 v16, v96, v3, -v16
	v_fma_f32 v4, v64, v3, -v4
	v_rcp_f32_e32 v3, v5
	v_rcp_f32_e32 v5, v9
	v_mul_f32_e32 v86, v70, v70
	v_fmac_f32_e32 v86, v72, v72
	v_fmac_f32_e32 v86, v71, v71
	v_mul_f32_e32 v5, s2, v5
	v_mul_f32_e32 v9, v17, v5
	v_fma_f32 v32, v129, v3, -v9
	v_mul_f32_e32 v9, v81, v5
	v_fma_f32 v17, v113, v3, -v9
	v_mul_f32_e32 v9, v49, v5
	v_mul_f32_e32 v5, v33, v5
	v_fma_f32 v9, v97, v3, -v9
	v_fma_f32 v5, v65, v3, -v5
	v_fmac_f32_e32 v86, v56, v56
	v_mul_f32_e32 v85, v74, v74
	v_fmac_f32_e32 v85, v83, v83
	v_fmac_f32_e32 v85, v73, v73
	s_nop 1
	v_add_f32_dpp v3, v138, v138 quad_perm:[1,0,3,2] row_mask:0xf bank_mask:0xf
	v_fmac_f32_e32 v85, v58, v58
	v_mul_f32_e32 v75, v42, v42
	v_fmac_f32_e32 v75, v57, v57
	v_fmac_f32_e32 v75, v41, v41
	s_nop 1
	v_add_f32_dpp v3, v3, v3 quad_perm:[2,3,0,1] row_mask:0xf bank_mask:0xf
	v_fmac_f32_e32 v75, v27, v27
	v_mul_f32_e32 v59, v25, v25
	v_fmac_f32_e32 v59, v26, v26
	v_fmac_f32_e32 v59, v24, v24
	s_nop 1
	v_add_f32_dpp v3, v3, v3 row_half_mirror row_mask:0xf bank_mask:0xf
	v_fmac_f32_e32 v59, v23, v23
	v_mul_f32_e32 v44, v12, v12
	v_fmac_f32_e32 v44, v13, v13
	v_fmac_f32_e32 v44, v11, v11
	s_nop 1
	v_add_f32_dpp v3, v3, v3 row_mirror row_mask:0xf bank_mask:0xf
	ds_swizzle_b32 v33, v3 offset:swizzle(SWAP,16)
	v_fmac_f32_e32 v44, v10, v10
	v_mul_f32_e32 v2, v14, v14
	v_fmac_f32_e32 v2, v29, v29
	v_fmac_f32_e32 v2, v28, v28
	s_waitcnt lgkmcnt(0)
	v_add_f32_e32 v3, v3, v33
	v_fmac_f32_e32 v2, v6, v6
	v_mul_f32_e32 v76, v15, v15
	v_fmac_f32_e32 v76, v43, v43
	v_fmac_f32_e32 v76, v30, v30
	s_nop 1
	v_add_f32_dpp v33, v115, v115 quad_perm:[1,0,3,2] row_mask:0xf bank_mask:0xf
	v_fmac_f32_e32 v76, v7, v7
	v_mul_f32_e32 v77, v8, v8
	v_fmac_f32_e32 v77, v31, v31
	v_fmac_f32_e32 v77, v16, v16
	s_nop 1
	v_add_f32_dpp v33, v33, v33 quad_perm:[2,3,0,1] row_mask:0xf bank_mask:0xf
	v_fmac_f32_e32 v77, v4, v4
	v_mul_f32_e32 v78, v17, v17
	v_fmac_f32_e32 v78, v32, v32
	v_fmac_f32_e32 v78, v9, v9
	s_nop 1
	v_add_f32_dpp v33, v33, v33 row_half_mirror row_mask:0xf bank_mask:0xf
	v_fmac_f32_e32 v78, v5, v5
	v_readlane_b32 s2, v255, 16
	v_readlane_b32 s3, v255, 17
	s_nop 1
	v_add_f32_dpp v33, v33, v33 row_mirror row_mask:0xf bank_mask:0xf
	ds_swizzle_b32 v45, v33 offset:swizzle(SWAP,16)
	s_cmp_eq_u32 s2, 0
	v_readlane_b32 s2, v255, 26
	v_lshlrev_b32_e32 v79, 2, v0
	v_readlane_b32 s3, v255, 27
	s_waitcnt lgkmcnt(0)
	v_add_f32_e32 v33, v33, v45
	v_fmamk_f32 v3, v3, 0x3c000000, v244
	s_cselect_b64 vcc, -1, 0
	s_lshl_b32 s36, s1, 1
	v_lshlrev_b32_e32 v0, 1, v0
	s_nop 1
	v_add_f32_dpp v45, v99, v99 quad_perm:[1,0,3,2] row_mask:0xf bank_mask:0xf
	s_nop 1
	v_add_f32_dpp v45, v45, v45 quad_perm:[2,3,0,1] row_mask:0xf bank_mask:0xf
	s_nop 1
	v_add_f32_dpp v45, v45, v45 row_half_mirror row_mask:0xf bank_mask:0xf
	s_nop 1
	v_add_f32_dpp v45, v45, v45 row_mirror row_mask:0xf bank_mask:0xf
	ds_swizzle_b32 v46, v45 offset:swizzle(SWAP,16)
	s_waitcnt lgkmcnt(0)
	v_add_f32_e32 v45, v45, v46
	s_nop 1
	v_add_f32_dpp v46, v84, v84 quad_perm:[1,0,3,2] row_mask:0xf bank_mask:0xf
	v_rsq_f32_e32 v84, v3
	s_nop 1
	v_add_f32_dpp v46, v46, v46 quad_perm:[2,3,0,1] row_mask:0xf bank_mask:0xf
	s_nop 1
	v_add_f32_dpp v46, v46, v46 row_half_mirror row_mask:0xf bank_mask:0xf
	s_nop 1
	v_add_f32_dpp v46, v46, v46 row_mirror row_mask:0xf bank_mask:0xf
	ds_swizzle_b32 v47, v46 offset:swizzle(SWAP,16)
	s_waitcnt lgkmcnt(0)
	v_add_f32_e32 v46, v46, v47
	s_nop 1
	v_add_f32_dpp v47, v101, v101 quad_perm:[1,0,3,2] row_mask:0xf bank_mask:0xf
	s_nop 1
	v_add_f32_dpp v47, v47, v47 quad_perm:[2,3,0,1] row_mask:0xf bank_mask:0xf
	s_nop 1
	v_add_f32_dpp v47, v47, v47 row_half_mirror row_mask:0xf bank_mask:0xf
	s_nop 1
	v_add_f32_dpp v47, v47, v47 row_mirror row_mask:0xf bank_mask:0xf
	ds_swizzle_b32 v48, v47 offset:swizzle(SWAP,16)
	s_waitcnt lgkmcnt(0)
	v_add_f32_e32 v47, v47, v48
	s_nop 1
	v_add_f32_dpp v48, v100, v100 quad_perm:[1,0,3,2] row_mask:0xf bank_mask:0xf
	s_nop 1
	v_add_f32_dpp v48, v48, v48 quad_perm:[2,3,0,1] row_mask:0xf bank_mask:0xf
	s_nop 1
	v_add_f32_dpp v48, v48, v48 row_half_mirror row_mask:0xf bank_mask:0xf
	s_nop 1
	v_add_f32_dpp v48, v48, v48 row_mirror row_mask:0xf bank_mask:0xf
	ds_swizzle_b32 v49, v48 offset:swizzle(SWAP,16)
	s_waitcnt lgkmcnt(0)
	v_add_f32_e32 v48, v48, v49
	s_nop 1
	v_add_f32_dpp v49, v87, v87 quad_perm:[1,0,3,2] row_mask:0xf bank_mask:0xf
	s_nop 1
	v_add_f32_dpp v49, v49, v49 quad_perm:[2,3,0,1] row_mask:0xf bank_mask:0xf
	s_nop 1
	v_add_f32_dpp v49, v49, v49 row_half_mirror row_mask:0xf bank_mask:0xf
	s_nop 1
	v_add_f32_dpp v49, v49, v49 row_mirror row_mask:0xf bank_mask:0xf
	ds_swizzle_b32 v60, v49 offset:swizzle(SWAP,16)
	s_waitcnt lgkmcnt(0)
	v_add_f32_e32 v60, v49, v60
	s_nop 1
	v_add_f32_dpp v49, v86, v86 quad_perm:[1,0,3,2] row_mask:0xf bank_mask:0xf
	s_nop 1
	v_add_f32_dpp v49, v49, v49 quad_perm:[2,3,0,1] row_mask:0xf bank_mask:0xf
	s_nop 1
	v_add_f32_dpp v49, v49, v49 row_half_mirror row_mask:0xf bank_mask:0xf
	s_nop 1
	v_add_f32_dpp v49, v49, v49 row_mirror row_mask:0xf bank_mask:0xf
	ds_swizzle_b32 v61, v49 offset:swizzle(SWAP,16)
	s_waitcnt lgkmcnt(0)
	v_add_f32_e32 v62, v49, v61
	s_nop 1
	v_add_f32_dpp v49, v85, v85 quad_perm:[1,0,3,2] row_mask:0xf bank_mask:0xf
	s_nop 1
	v_add_f32_dpp v49, v49, v49 quad_perm:[2,3,0,1] row_mask:0xf bank_mask:0xf
	s_nop 1
	v_add_f32_dpp v49, v49, v49 row_half_mirror row_mask:0xf bank_mask:0xf
	s_nop 1
	v_add_f32_dpp v49, v49, v49 row_mirror row_mask:0xf bank_mask:0xf
	ds_swizzle_b32 v61, v49 offset:swizzle(SWAP,16)
	s_waitcnt lgkmcnt(0)
	v_add_f32_e32 v64, v49, v61
	s_nop 1
	v_add_f32_dpp v49, v75, v75 quad_perm:[1,0,3,2] row_mask:0xf bank_mask:0xf
	s_nop 1
	v_add_f32_dpp v49, v49, v49 quad_perm:[2,3,0,1] row_mask:0xf bank_mask:0xf
	s_nop 1
	v_add_f32_dpp v49, v49, v49 row_half_mirror row_mask:0xf bank_mask:0xf
	s_nop 1
	v_add_f32_dpp v49, v49, v49 row_mirror row_mask:0xf bank_mask:0xf
	ds_swizzle_b32 v61, v49 offset:swizzle(SWAP,16)
	s_waitcnt lgkmcnt(0)
	v_add_f32_e32 v75, v49, v61
	s_nop 1
	v_add_f32_dpp v49, v59, v59 quad_perm:[1,0,3,2] row_mask:0xf bank_mask:0xf
	s_nop 1
	v_add_f32_dpp v49, v49, v49 quad_perm:[2,3,0,1] row_mask:0xf bank_mask:0xf
	s_nop 1
	v_add_f32_dpp v49, v49, v49 row_half_mirror row_mask:0xf bank_mask:0xf
	s_nop 1
	v_add_f32_dpp v49, v49, v49 row_mirror row_mask:0xf bank_mask:0xf
	ds_swizzle_b32 v59, v49 offset:swizzle(SWAP,16)
	s_waitcnt lgkmcnt(0)
	v_add_f32_e32 v65, v49, v59
	s_nop 1
	v_add_f32_dpp v44, v44, v44 quad_perm:[1,0,3,2] row_mask:0xf bank_mask:0xf
	s_nop 1
	v_add_f32_dpp v44, v44, v44 quad_perm:[2,3,0,1] row_mask:0xf bank_mask:0xf
	s_nop 1
	v_add_f32_dpp v44, v44, v44 row_half_mirror row_mask:0xf bank_mask:0xf
	s_nop 1
	v_add_f32_dpp v44, v44, v44 row_mirror row_mask:0xf bank_mask:0xf
	ds_swizzle_b32 v49, v44 offset:swizzle(SWAP,16)
	s_waitcnt lgkmcnt(0)
	v_add_f32_e32 v63, v44, v49
	s_nop 1
	v_add_f32_dpp v2, v2, v2 quad_perm:[1,0,3,2] row_mask:0xf bank_mask:0xf
	s_nop 1
	v_add_f32_dpp v2, v2, v2 quad_perm:[2,3,0,1] row_mask:0xf bank_mask:0xf
	s_nop 1
	v_add_f32_dpp v2, v2, v2 row_half_mirror row_mask:0xf bank_mask:0xf
	s_nop 1
	v_add_f32_dpp v2, v2, v2 row_mirror row_mask:0xf bank_mask:0xf
	ds_swizzle_b32 v44, v2 offset:swizzle(SWAP,16)
	s_waitcnt lgkmcnt(0)
	v_add_f32_e32 v61, v2, v44
	s_nop 1
	v_add_f32_dpp v2, v76, v76 quad_perm:[1,0,3,2] row_mask:0xf bank_mask:0xf
	global_load_dword v76, v79, s[2:3]
	s_nop 1
	v_add_f32_dpp v2, v2, v2 quad_perm:[2,3,0,1] row_mask:0xf bank_mask:0xf
	s_nop 1
	v_add_f32_dpp v2, v2, v2 row_half_mirror row_mask:0xf bank_mask:0xf
	s_nop 1
	v_add_f32_dpp v2, v2, v2 row_mirror row_mask:0xf bank_mask:0xf
	ds_swizzle_b32 v44, v2 offset:swizzle(SWAP,16)
	s_waitcnt lgkmcnt(0)
	v_add_f32_e32 v59, v2, v44
	s_nop 1
	v_add_f32_dpp v2, v77, v77 quad_perm:[1,0,3,2] row_mask:0xf bank_mask:0xf
	global_load_dword v77, v79, s[2:3] offset:128
	s_nop 1
	v_add_f32_dpp v2, v2, v2 quad_perm:[2,3,0,1] row_mask:0xf bank_mask:0xf
	s_nop 1
	v_add_f32_dpp v2, v2, v2 row_half_mirror row_mask:0xf bank_mask:0xf
	s_nop 1
	v_add_f32_dpp v2, v2, v2 row_mirror row_mask:0xf bank_mask:0xf
	ds_swizzle_b32 v44, v2 offset:swizzle(SWAP,16)
	s_waitcnt lgkmcnt(0)
	v_add_f32_e32 v49, v2, v44
	s_nop 1
	v_add_f32_dpp v2, v78, v78 quad_perm:[1,0,3,2] row_mask:0xf bank_mask:0xf
	global_load_dword v78, v79, s[2:3] offset:256
	global_load_dword v79, v79, s[2:3] offset:384
	v_readlane_b32 s2, v254, 63
	v_readlane_b32 s3, v255, 0
	s_nop 1
	v_add_f32_dpp v2, v2, v2 quad_perm:[2,3,0,1] row_mask:0xf bank_mask:0xf
	s_nop 1
	v_add_f32_dpp v2, v2, v2 row_half_mirror row_mask:0xf bank_mask:0xf
	s_nop 1
	v_add_f32_dpp v2, v2, v2 row_mirror row_mask:0xf bank_mask:0xf
	ds_swizzle_b32 v44, v2 offset:swizzle(SWAP,16)
	s_waitcnt lgkmcnt(0)
	v_add_f32_e32 v44, v2, v44
	v_cndmask_b32_e32 v2, v252, v246, vcc
	s_waitcnt vmcnt(3)
	v_mul_f32_e32 v76, v76, v2
	s_waitcnt vmcnt(2)
	v_mul_f32_e32 v77, v2, v77
	s_waitcnt vmcnt(1)
	v_mul_f32_e32 v78, v2, v78
	s_waitcnt vmcnt(0)
	v_mul_f32_e32 v79, v2, v79
	v_lshl_add_u32 v2, v134, 2, s0
	v_ashrrev_i32_e32 v3, 31, v2
	v_lshlrev_b64 v[80:81], 11, v[2:3]
	v_mul_f32_e32 v3, v137, v84
	v_lshl_add_u64 v[80:81], s[2:3], 0, v[80:81]
	v_mul_f32_e32 v3, v3, v76
	v_lshl_add_u64 v[80:81], v[80:81], 0, s[36:37]
	v_bfe_u32 v85, v3, 16, 1
	v_lshl_add_u64 v[80:81], v[80:81], 0, v[0:1]
	v_add3_u32 v3, v3, v85, s86
	global_store_short_d16_hi v[80:81], v3, off offset:1024
	v_mul_f32_e32 v3, v136, v84
	v_mul_f32_e32 v3, v3, v77
	v_bfe_u32 v85, v3, 16, 1
	v_add3_u32 v3, v3, v85, s86
	global_store_short_d16_hi v[80:81], v3, off offset:1088
	v_mul_f32_e32 v3, v135, v84
	v_mul_f32_e32 v3, v3, v78
	v_bfe_u32 v85, v3, 16, 1
	v_add3_u32 v3, v3, v85, s86
	global_store_short_d16_hi v[80:81], v3, off offset:1152
	v_mul_f32_e32 v3, v114, v84
	v_mul_f32_e32 v3, v3, v79
	v_bfe_u32 v84, v3, 16, 1
	v_add3_u32 v3, v3, v84, s86
	global_store_short_d16_hi v[80:81], v3, off offset:1216
	v_fmamk_f32 v3, v33, 0x3c000000, v244
	v_rsq_f32_e32 v3, v3
	v_or_b32_e32 v80, 1, v2
	v_ashrrev_i32_e32 v81, 31, v80
	v_lshlrev_b64 v[80:81], 11, v[80:81]
	v_mul_f32_e32 v33, v98, v3
	v_lshl_add_u64 v[80:81], s[2:3], 0, v[80:81]
	v_mul_f32_e32 v33, v33, v76
	v_lshl_add_u64 v[80:81], v[80:81], 0, s[36:37]
	v_bfe_u32 v84, v33, 16, 1
	v_lshl_add_u64 v[80:81], v[80:81], 0, v[0:1]
	v_add3_u32 v33, v33, v84, s86
	global_store_short_d16_hi v[80:81], v33, off offset:1024
	v_mul_f32_e32 v33, v82, v3
	v_mul_f32_e32 v33, v33, v77
	v_bfe_u32 v82, v33, 16, 1
	v_add3_u32 v33, v33, v82, s86
	global_store_short_d16_hi v[80:81], v33, off offset:1088
	v_mul_f32_e32 v33, v67, v3
	v_mul_f32_e32 v33, v33, v78
	v_bfe_u32 v67, v33, 16, 1
	v_mul_f32_e32 v3, v66, v3
	v_add3_u32 v33, v33, v67, s86
	v_mul_f32_e32 v3, v3, v79
	global_store_short_d16_hi v[80:81], v33, off offset:1152
	v_bfe_u32 v33, v3, 16, 1
	v_add3_u32 v3, v3, v33, s86
	global_store_short_d16_hi v[80:81], v3, off offset:1216
	v_fmamk_f32 v3, v45, 0x3c000000, v244
	v_rsq_f32_e32 v3, v3
	v_or_b32_e32 v66, 2, v2
	v_ashrrev_i32_e32 v67, 31, v66
	v_lshlrev_b64 v[66:67], 11, v[66:67]
	v_mul_f32_e32 v33, v51, v3
	v_lshl_add_u64 v[66:67], s[2:3], 0, v[66:67]
	v_mul_f32_e32 v33, v33, v76
	v_lshl_add_u64 v[66:67], v[66:67], 0, s[36:37]
	v_bfe_u32 v45, v33, 16, 1
	v_lshl_add_u64 v[66:67], v[66:67], 0, v[0:1]
	v_add3_u32 v33, v33, v45, s86
	global_store_short_d16_hi v[66:67], v33, off offset:1024
	v_mul_f32_e32 v33, v50, v3
	v_mul_f32_e32 v33, v33, v77
	v_bfe_u32 v45, v33, 16, 1
	v_add3_u32 v33, v33, v45, s86
	global_store_short_d16_hi v[66:67], v33, off offset:1088
	v_mul_f32_e32 v33, v36, v3
	v_mul_f32_e32 v33, v33, v78
	v_bfe_u32 v36, v33, 16, 1
	v_mul_f32_e32 v3, v35, v3
	v_add3_u32 v33, v33, v36, s86
	v_mul_f32_e32 v3, v3, v79
	global_store_short_d16_hi v[66:67], v33, off offset:1152
	v_bfe_u32 v33, v3, 16, 1
	v_add3_u32 v3, v3, v33, s86
	global_store_short_d16_hi v[66:67], v3, off offset:1216
	v_fmamk_f32 v3, v46, 0x3c000000, v244
	v_rsq_f32_e32 v3, v3
	v_or_b32_e32 v50, 3, v2
	v_ashrrev_i32_e32 v51, 31, v50
	v_lshlrev_b64 v[50:51], 11, v[50:51]
	v_mul_f32_e32 v33, v34, v3
	v_mul_f32_e32 v20, v20, v3
	v_mul_f32_e32 v19, v19, v3
	v_mul_f32_e32 v3, v18, v3
	v_lshl_add_u64 v[50:51], s[2:3], 0, v[50:51]
	v_mul_f32_e32 v33, v33, v76
	v_mul_f32_e32 v3, v3, v79
	v_lshl_add_u64 v[50:51], v[50:51], 0, s[36:37]
	v_bfe_u32 v34, v33, 16, 1
	v_bfe_u32 v18, v3, 16, 1
	v_lshl_add_u64 v[50:51], v[50:51], 0, v[0:1]
	v_add3_u32 v33, v33, v34, s86
	v_mul_f32_e32 v20, v20, v77
	v_add3_u32 v3, v3, v18, s86
	global_store_short_d16_hi v[50:51], v33, off offset:1024
	v_bfe_u32 v33, v20, 16, 1
	global_store_short_d16_hi v[50:51], v3, off offset:1216
	v_fmamk_f32 v3, v47, 0x3c000000, v244
	v_add3_u32 v20, v20, v33, s86
	v_mul_f32_e32 v19, v19, v78
	v_rsq_f32_e32 v3, v3
	global_store_short_d16_hi v[50:51], v20, off offset:1088
	v_bfe_u32 v20, v19, 16, 1
	v_add3_u32 v19, v19, v20, s86
	v_add_u32_e32 v18, 8, v2
	global_store_short_d16_hi v[50:51], v19, off offset:1152
	v_ashrrev_i32_e32 v19, 31, v18
	v_lshlrev_b64 v[18:19], 11, v[18:19]
	v_mul_f32_e32 v20, v52, v3
	v_lshl_add_u64 v[18:19], s[2:3], 0, v[18:19]
	v_mul_f32_e32 v20, v20, v76
	v_lshl_add_u64 v[18:19], v[18:19], 0, s[36:37]
	v_bfe_u32 v33, v20, 16, 1
	v_lshl_add_u64 v[18:19], v[18:19], 0, v[0:1]
	v_add3_u32 v20, v20, v33, s86
	global_store_short_d16_hi v[18:19], v20, off offset:1024
	v_mul_f32_e32 v20, v37, v3
	v_mul_f32_e32 v20, v20, v77
	v_bfe_u32 v33, v20, 16, 1
	v_add3_u32 v20, v20, v33, s86
	global_store_short_d16_hi v[18:19], v20, off offset:1088
	v_mul_f32_e32 v20, v38, v3
	v_mul_f32_e32 v20, v20, v78
	v_bfe_u32 v33, v20, 16, 1
	v_mul_f32_e32 v3, v21, v3
	v_add3_u32 v20, v20, v33, s86
	v_mul_f32_e32 v3, v3, v79
	global_store_short_d16_hi v[18:19], v20, off offset:1152
	v_bfe_u32 v20, v3, 16, 1
	v_add3_u32 v3, v3, v20, s86
	global_store_short_d16_hi v[18:19], v3, off offset:1216
	v_fmamk_f32 v3, v48, 0x3c000000, v244
	v_rsq_f32_e32 v3, v3
	v_add_u32_e32 v18, 9, v2
	v_ashrrev_i32_e32 v19, 31, v18
	v_lshlrev_b64 v[18:19], 11, v[18:19]
	v_mul_f32_e32 v20, v54, v3
	v_lshl_add_u64 v[18:19], s[2:3], 0, v[18:19]
	v_mul_f32_e32 v20, v20, v76
	v_lshl_add_u64 v[18:19], v[18:19], 0, s[36:37]
	v_bfe_u32 v21, v20, 16, 1
	v_lshl_add_u64 v[18:19], v[18:19], 0, v[0:1]
	v_add3_u32 v20, v20, v21, s86
	global_store_short_d16_hi v[18:19], v20, off offset:1024
	v_mul_f32_e32 v20, v53, v3
	v_mul_f32_e32 v20, v20, v77
	v_bfe_u32 v21, v20, 16, 1
	v_add3_u32 v20, v20, v21, s86
	global_store_short_d16_hi v[18:19], v20, off offset:1088
	v_mul_f32_e32 v20, v39, v3
	v_mul_f32_e32 v20, v20, v78
	v_bfe_u32 v21, v20, 16, 1
	v_mul_f32_e32 v3, v22, v3
	v_add3_u32 v20, v20, v21, s86
	v_mul_f32_e32 v3, v3, v79
	global_store_short_d16_hi v[18:19], v20, off offset:1152
	v_bfe_u32 v20, v3, 16, 1
	v_add3_u32 v3, v3, v20, s86
	global_store_short_d16_hi v[18:19], v3, off offset:1216
	v_fmamk_f32 v3, v60, 0x3c000000, v244
	v_rsq_f32_e32 v3, v3
	v_add_u32_e32 v18, 10, v2
	v_ashrrev_i32_e32 v19, 31, v18
	v_lshlrev_b64 v[18:19], 11, v[18:19]
	v_mul_f32_e32 v20, v69, v3
	v_lshl_add_u64 v[18:19], s[2:3], 0, v[18:19]
	v_mul_f32_e32 v20, v20, v76
	v_lshl_add_u64 v[18:19], v[18:19], 0, s[36:37]
	v_bfe_u32 v21, v20, 16, 1
	v_lshl_add_u64 v[18:19], v[18:19], 0, v[0:1]
	v_add3_u32 v20, v20, v21, s86
	global_store_short_d16_hi v[18:19], v20, off offset:1024
	v_mul_f32_e32 v20, v55, v3
	v_mul_f32_e32 v20, v20, v77
	v_bfe_u32 v21, v20, 16, 1
	v_add3_u32 v20, v20, v21, s86
	global_store_short_d16_hi v[18:19], v20, off offset:1088
	v_mul_f32_e32 v20, v68, v3
	v_mul_f32_e32 v20, v20, v78
	v_bfe_u32 v21, v20, 16, 1
	v_mul_f32_e32 v3, v40, v3
	v_add3_u32 v20, v20, v21, s86
	v_mul_f32_e32 v3, v3, v79
	global_store_short_d16_hi v[18:19], v20, off offset:1152
	v_bfe_u32 v20, v3, 16, 1
	v_add3_u32 v3, v3, v20, s86
	global_store_short_d16_hi v[18:19], v3, off offset:1216
	v_fmamk_f32 v3, v62, 0x3c000000, v244
	v_rsq_f32_e32 v3, v3
	v_add_u32_e32 v18, 11, v2
	v_ashrrev_i32_e32 v19, 31, v18
	v_lshlrev_b64 v[18:19], 11, v[18:19]
	v_mul_f32_e32 v20, v72, v3
	v_lshl_add_u64 v[18:19], s[2:3], 0, v[18:19]
	v_mul_f32_e32 v20, v20, v76
	v_lshl_add_u64 v[18:19], v[18:19], 0, s[36:37]
	v_bfe_u32 v21, v20, 16, 1
	v_lshl_add_u64 v[18:19], v[18:19], 0, v[0:1]
	v_add3_u32 v20, v20, v21, s86
	global_store_short_d16_hi v[18:19], v20, off offset:1024
	v_mul_f32_e32 v20, v70, v3
	v_mul_f32_e32 v20, v20, v77
	v_bfe_u32 v21, v20, 16, 1
	v_add3_u32 v20, v20, v21, s86
	global_store_short_d16_hi v[18:19], v20, off offset:1088
	v_mul_f32_e32 v20, v71, v3
	v_mul_f32_e32 v20, v20, v78
	v_bfe_u32 v21, v20, 16, 1
	v_mul_f32_e32 v3, v56, v3
	v_add3_u32 v20, v20, v21, s86
	v_mul_f32_e32 v3, v3, v79
	global_store_short_d16_hi v[18:19], v20, off offset:1152
	v_bfe_u32 v20, v3, 16, 1
	v_add3_u32 v3, v3, v20, s86
	global_store_short_d16_hi v[18:19], v3, off offset:1216
	v_fmamk_f32 v3, v64, 0x3c000000, v244
	v_rsq_f32_e32 v3, v3
	v_add_u32_e32 v18, 16, v2
	v_ashrrev_i32_e32 v19, 31, v18
	v_lshlrev_b64 v[18:19], 11, v[18:19]
	v_mul_f32_e32 v20, v83, v3
	v_lshl_add_u64 v[18:19], s[2:3], 0, v[18:19]
	v_mul_f32_e32 v20, v20, v76
	v_lshl_add_u64 v[18:19], v[18:19], 0, s[36:37]
	v_bfe_u32 v21, v20, 16, 1
	v_lshl_add_u64 v[18:19], v[18:19], 0, v[0:1]
	v_add3_u32 v20, v20, v21, s86
	global_store_short_d16_hi v[18:19], v20, off offset:1024
	v_mul_f32_e32 v20, v74, v3
	v_mul_f32_e32 v20, v20, v77
	v_bfe_u32 v21, v20, 16, 1
	v_add3_u32 v20, v20, v21, s86
	global_store_short_d16_hi v[18:19], v20, off offset:1088
	v_mul_f32_e32 v20, v73, v3
	v_mul_f32_e32 v20, v20, v78
	v_bfe_u32 v21, v20, 16, 1
	v_mul_f32_e32 v3, v58, v3
	v_add3_u32 v20, v20, v21, s86
	v_mul_f32_e32 v3, v3, v79
	global_store_short_d16_hi v[18:19], v20, off offset:1152
	v_bfe_u32 v20, v3, 16, 1
	v_add3_u32 v3, v3, v20, s86
	global_store_short_d16_hi v[18:19], v3, off offset:1216
	v_fmamk_f32 v3, v75, 0x3c000000, v244
	v_rsq_f32_e32 v3, v3
	v_add_u32_e32 v18, 17, v2
	v_ashrrev_i32_e32 v19, 31, v18
	v_lshlrev_b64 v[18:19], 11, v[18:19]
	v_mul_f32_e32 v20, v57, v3
	v_lshl_add_u64 v[18:19], s[2:3], 0, v[18:19]
	v_mul_f32_e32 v20, v20, v76
	v_lshl_add_u64 v[18:19], v[18:19], 0, s[36:37]
	v_bfe_u32 v21, v20, 16, 1
	v_lshl_add_u64 v[18:19], v[18:19], 0, v[0:1]
	v_add3_u32 v20, v20, v21, s86
	global_store_short_d16_hi v[18:19], v20, off offset:1024
	v_mul_f32_e32 v20, v42, v3
	v_mul_f32_e32 v20, v20, v77
	v_bfe_u32 v21, v20, 16, 1
	v_add3_u32 v20, v20, v21, s86
	global_store_short_d16_hi v[18:19], v20, off offset:1088
	v_mul_f32_e32 v20, v41, v3
	v_mul_f32_e32 v20, v20, v78
	v_bfe_u32 v21, v20, 16, 1
	v_mul_f32_e32 v3, v27, v3
	v_add3_u32 v20, v20, v21, s86
	v_mul_f32_e32 v3, v3, v79
	global_store_short_d16_hi v[18:19], v20, off offset:1152
	v_bfe_u32 v20, v3, 16, 1
	v_add3_u32 v3, v3, v20, s86
	global_store_short_d16_hi v[18:19], v3, off offset:1216
	v_fmamk_f32 v3, v65, 0x3c000000, v244
	v_rsq_f32_e32 v3, v3
	v_add_u32_e32 v18, 18, v2
	v_ashrrev_i32_e32 v19, 31, v18
	v_lshlrev_b64 v[18:19], 11, v[18:19]
	v_mul_f32_e32 v20, v26, v3
	v_lshl_add_u64 v[18:19], s[2:3], 0, v[18:19]
	v_mul_f32_e32 v20, v20, v76
	v_lshl_add_u64 v[18:19], v[18:19], 0, s[36:37]
	v_bfe_u32 v21, v20, 16, 1
	v_lshl_add_u64 v[18:19], v[18:19], 0, v[0:1]
	v_add3_u32 v20, v20, v21, s86
	global_store_short_d16_hi v[18:19], v20, off offset:1024
	v_mul_f32_e32 v20, v25, v3
	v_mul_f32_e32 v20, v20, v77
	v_bfe_u32 v21, v20, 16, 1
	v_add3_u32 v20, v20, v21, s86
	global_store_short_d16_hi v[18:19], v20, off offset:1088
	v_mul_f32_e32 v20, v24, v3
	v_mul_f32_e32 v20, v20, v78
	v_bfe_u32 v21, v20, 16, 1
	v_mul_f32_e32 v3, v23, v3
	v_add3_u32 v20, v20, v21, s86
	v_mul_f32_e32 v3, v3, v79
	global_store_short_d16_hi v[18:19], v20, off offset:1152
	v_bfe_u32 v20, v3, 16, 1
	v_add3_u32 v3, v3, v20, s86
	global_store_short_d16_hi v[18:19], v3, off offset:1216
	v_fmamk_f32 v3, v63, 0x3c000000, v244
	v_rsq_f32_e32 v3, v3
	v_add_u32_e32 v18, 19, v2
	v_ashrrev_i32_e32 v19, 31, v18
	v_lshlrev_b64 v[18:19], 11, v[18:19]
	v_mul_f32_e32 v13, v13, v3
	v_mul_f32_e32 v12, v12, v3
	v_mul_f32_e32 v11, v11, v3
	v_mul_f32_e32 v3, v10, v3
	v_lshl_add_u64 v[18:19], s[2:3], 0, v[18:19]
	v_mul_f32_e32 v13, v13, v76
	v_mul_f32_e32 v3, v3, v79
	v_lshl_add_u64 v[18:19], v[18:19], 0, s[36:37]
	v_bfe_u32 v20, v13, 16, 1
	v_bfe_u32 v10, v3, 16, 1
	v_lshl_add_u64 v[18:19], v[18:19], 0, v[0:1]
	v_add3_u32 v13, v13, v20, s86
	v_mul_f32_e32 v12, v12, v77
	v_add3_u32 v3, v3, v10, s86
	global_store_short_d16_hi v[18:19], v13, off offset:1024
	v_bfe_u32 v13, v12, 16, 1
	global_store_short_d16_hi v[18:19], v3, off offset:1216
	v_fmamk_f32 v3, v61, 0x3c000000, v244
	v_add3_u32 v12, v12, v13, s86
	v_mul_f32_e32 v11, v11, v78
	v_rsq_f32_e32 v3, v3
	global_store_short_d16_hi v[18:19], v12, off offset:1088
	v_bfe_u32 v12, v11, 16, 1
	v_add3_u32 v11, v11, v12, s86
	v_add_u32_e32 v10, 24, v2
	global_store_short_d16_hi v[18:19], v11, off offset:1152
	v_ashrrev_i32_e32 v11, 31, v10
	v_lshlrev_b64 v[10:11], 11, v[10:11]
	v_mul_f32_e32 v12, v29, v3
	v_lshl_add_u64 v[10:11], s[2:3], 0, v[10:11]
	v_mul_f32_e32 v12, v12, v76
	v_lshl_add_u64 v[10:11], v[10:11], 0, s[36:37]
	v_bfe_u32 v13, v12, 16, 1
	v_lshl_add_u64 v[10:11], v[10:11], 0, v[0:1]
	v_add3_u32 v12, v12, v13, s86
	global_store_short_d16_hi v[10:11], v12, off offset:1024
	v_mul_f32_e32 v12, v14, v3
	v_mul_f32_e32 v12, v12, v77
	v_bfe_u32 v13, v12, 16, 1
	v_add3_u32 v12, v12, v13, s86
	global_store_short_d16_hi v[10:11], v12, off offset:1088
	v_mul_f32_e32 v12, v28, v3
	v_mul_f32_e32 v3, v6, v3
	v_mul_f32_e32 v3, v3, v79
	v_bfe_u32 v6, v3, 16, 1
	v_add3_u32 v3, v3, v6, s86
	v_mul_f32_e32 v12, v12, v78
	global_store_short_d16_hi v[10:11], v3, off offset:1216
	v_fmamk_f32 v3, v59, 0x3c000000, v244
	v_bfe_u32 v13, v12, 16, 1
	v_rsq_f32_e32 v3, v3
	v_add3_u32 v12, v12, v13, s86
	global_store_short_d16_hi v[10:11], v12, off offset:1152
	v_add_u32_e32 v10, 25, v2
	v_ashrrev_i32_e32 v11, 31, v10
	v_lshlrev_b64 v[10:11], 11, v[10:11]
	v_mul_f32_e32 v6, v43, v3
	v_lshl_add_u64 v[10:11], s[2:3], 0, v[10:11]
	v_mul_f32_e32 v6, v6, v76
	v_lshl_add_u64 v[10:11], v[10:11], 0, s[36:37]
	v_bfe_u32 v12, v6, 16, 1
	v_lshl_add_u64 v[10:11], v[10:11], 0, v[0:1]
	v_add3_u32 v6, v6, v12, s86
	global_store_short_d16_hi v[10:11], v6, off offset:1024
	v_mul_f32_e32 v6, v15, v3
	v_mul_f32_e32 v6, v6, v77
	v_bfe_u32 v12, v6, 16, 1
	v_add3_u32 v6, v6, v12, s86
	global_store_short_d16_hi v[10:11], v6, off offset:1088
	v_mul_f32_e32 v6, v30, v3
	v_mul_f32_e32 v6, v6, v78
	v_bfe_u32 v12, v6, 16, 1
	v_mul_f32_e32 v3, v7, v3
	v_add3_u32 v6, v6, v12, s86
	v_mul_f32_e32 v3, v3, v79
	global_store_short_d16_hi v[10:11], v6, off offset:1152
	v_bfe_u32 v6, v3, 16, 1
	v_add3_u32 v3, v3, v6, s86
	global_store_short_d16_hi v[10:11], v3, off offset:1216
	v_fmamk_f32 v3, v49, 0x3c000000, v244
	v_rsq_f32_e32 v3, v3
	v_add_u32_e32 v6, 26, v2
	v_ashrrev_i32_e32 v7, 31, v6
	v_lshlrev_b64 v[6:7], 11, v[6:7]
	v_mul_f32_e32 v10, v31, v3
	v_lshl_add_u64 v[6:7], s[2:3], 0, v[6:7]
	v_mul_f32_e32 v10, v10, v76
	v_lshl_add_u64 v[6:7], v[6:7], 0, s[36:37]
	v_bfe_u32 v11, v10, 16, 1
	v_mul_f32_e32 v8, v8, v3
	v_lshl_add_u64 v[6:7], v[6:7], 0, v[0:1]
	v_add3_u32 v10, v10, v11, s86
	v_mul_f32_e32 v8, v8, v77
	global_store_short_d16_hi v[6:7], v10, off offset:1024
	v_bfe_u32 v10, v8, 16, 1
	v_add3_u32 v8, v8, v10, s86
	global_store_short_d16_hi v[6:7], v8, off offset:1088
	v_mul_f32_e32 v8, v16, v3
	v_mul_f32_e32 v3, v4, v3
	v_mul_f32_e32 v3, v3, v79
	v_bfe_u32 v4, v3, 16, 1
	v_add3_u32 v3, v3, v4, s86
	global_store_short_d16_hi v[6:7], v3, off offset:1216
	v_fmamk_f32 v3, v44, 0x3c000000, v244
	v_add_u32_e32 v2, 27, v2
	v_rsq_f32_e32 v4, v3
	v_ashrrev_i32_e32 v3, 31, v2
	v_lshlrev_b64 v[2:3], 11, v[2:3]
	v_lshl_add_u64 v[2:3], s[2:3], 0, v[2:3]
	v_mul_f32_e32 v8, v8, v78
	v_lshl_add_u64 v[2:3], v[2:3], 0, s[36:37]
	v_bfe_u32 v10, v8, 16, 1
	v_lshl_add_u64 v[2:3], v[2:3], 0, v[0:1]
	v_mul_f32_e32 v0, v32, v4
	v_add3_u32 v8, v8, v10, s86
	v_mul_f32_e32 v0, v76, v0
	global_store_short_d16_hi v[6:7], v8, off offset:1152
	v_bfe_u32 v6, v0, 16, 1
	v_add3_u32 v0, v0, v6, s86
	global_store_short_d16_hi v[2:3], v0, off offset:1024
	v_mul_f32_e32 v0, v17, v4
	v_mul_f32_e32 v0, v77, v0
	v_bfe_u32 v6, v0, 16, 1
	v_add3_u32 v0, v0, v6, s86
	global_store_short_d16_hi v[2:3], v0, off offset:1088
	v_mul_f32_e32 v0, v9, v4
	v_mul_f32_e32 v0, v78, v0
	v_bfe_u32 v6, v0, 16, 1
	v_add3_u32 v0, v0, v6, s86
	global_store_short_d16_hi v[2:3], v0, off offset:1152
	v_mul_f32_e32 v0, v5, v4
	v_mul_f32_e32 v0, v79, v0
	v_bfe_u32 v4, v0, 16, 1
	v_add3_u32 v0, v0, v4, s86
	global_store_short_d16_hi v[2:3], v0, off offset:1216
	s_waitcnt lgkmcnt(0)
	s_barrier

.LBB0_779:
	v_mbcnt_lo_u32_b32 v0, -1, 0
	v_mbcnt_hi_u32_b32 v0, -1, v0
	s_nop 0
	v_cmp_gt_u32_e32 vcc, 32, v0
	s_and_saveexec_b64 s[4:5], vcc
	v_lshl_add_u32 v130, v0, 2, s14
	ds_write2_b32 v130, v204, v205 offset0:64 offset1:96
	s_or_b64 exec, exec, s[4:5]
	v_ashrrev_i32_e32 v134, 5, v0
	s_waitcnt lgkmcnt(0)
	v_lshl_add_u32 v139, v134, 4, s14
	ds_read_b128 v[140:143], v139 offset:256
	ds_read_b128 v[130:133], v139 offset:288
	ds_read_b128 v[144:147], v139 offset:384
	v_readlane_b32 s2, v255, 35
	v_and_b32_e32 v0, 31, v0
	s_waitcnt lgkmcnt(2)
	v_rcp_f32_e32 v140, v140
	s_waitcnt lgkmcnt(0)
	v_rcp_f32_e32 v135, v144
	s_nop 0
	v_mul_f32_e32 v144, s2, v135
	v_mul_f32_e32 v2, v2, v144
	v_fma_f32 v137, v114, v140, -v2
	v_mul_f32_e32 v2, v66, v144
	v_fma_f32 v136, v98, v140, -v2
	v_mul_f32_e32 v2, v34, v144
	v_fma_f32 v135, v82, v140, -v2
	v_mul_f32_e32 v2, v18, v144
	v_rcp_f32_e32 v18, v145
	v_fma_f32 v114, v50, v140, -v2
	v_rcp_f32_e32 v2, v141
	v_mul_f32_e32 v138, v136, v136
	v_mul_f32_e32 v18, s2, v18
	v_mul_f32_e32 v3, v3, v18
	v_fma_f32 v98, v115, v2, -v3
	v_mul_f32_e32 v3, v67, v18
	v_fma_f32 v82, v99, v2, -v3
	v_mul_f32_e32 v3, v35, v18
	v_fma_f32 v67, v83, v2, -v3
	v_mul_f32_e32 v3, v19, v18
	v_fma_f32 v66, v51, v2, -v3
	v_rcp_f32_e32 v3, v146
	v_rcp_f32_e32 v2, v142
	v_fmac_f32_e32 v138, v137, v137
	v_fmac_f32_e32 v138, v135, v135
	v_mul_f32_e32 v3, s2, v3
	v_mul_f32_e32 v4, v4, v3
	v_fma_f32 v51, v116, v2, -v4
	v_mul_f32_e32 v4, v68, v3
	v_fma_f32 v50, v100, v2, -v4
	v_mul_f32_e32 v4, v36, v3
	v_mul_f32_e32 v3, v20, v3
	v_fma_f32 v35, v52, v2, -v3
	v_rcp_f32_e32 v3, v147
	v_fma_f32 v36, v84, v2, -v4
	v_rcp_f32_e32 v2, v143
	v_fmac_f32_e32 v138, v114, v114
	v_mul_f32_e32 v3, s2, v3
	v_mul_f32_e32 v4, v5, v3
	v_fma_f32 v34, v117, v2, -v4
	v_mul_f32_e32 v4, v69, v3
	v_fma_f32 v20, v101, v2, -v4
	v_mul_f32_e32 v4, v37, v3
	v_mul_f32_e32 v3, v21, v3
	v_fma_f32 v19, v85, v2, -v4
	v_fma_f32 v18, v53, v2, -v3
	ds_read_b128 v[2:5], v139 offset:416
	v_rcp_f32_e32 v21, v130
	v_mul_f32_e32 v115, v82, v82
	v_fmac_f32_e32 v115, v98, v98
	v_fmac_f32_e32 v115, v67, v67
	s_waitcnt lgkmcnt(0)
	v_rcp_f32_e32 v2, v2
	v_rcp_f32_e32 v3, v3
	v_fmac_f32_e32 v115, v66, v66
	v_mul_f32_e32 v100, v50, v50
	v_mul_f32_e32 v2, s2, v2
	v_mul_f32_e32 v6, v6, v2
	v_fma_f32 v68, v118, v21, -v6
	v_mul_f32_e32 v6, v70, v2
	v_fma_f32 v52, v102, v21, -v6
	v_mul_f32_e32 v6, v38, v2
	v_mul_f32_e32 v2, v22, v2
	v_fma_f32 v37, v54, v21, -v2
	v_rcp_f32_e32 v2, v131
	v_mul_f32_e32 v3, s2, v3
	v_fma_f32 v53, v86, v21, -v6
	v_mul_f32_e32 v6, v7, v3
	v_fma_f32 v83, v119, v2, -v6
	v_mul_f32_e32 v6, v71, v3
	v_fma_f32 v69, v103, v2, -v6
	v_mul_f32_e32 v6, v39, v3
	v_mul_f32_e32 v3, v23, v3
	v_fma_f32 v54, v55, v2, -v3
	v_rcp_f32_e32 v3, v4
	v_fma_f32 v70, v87, v2, -v6
	v_rcp_f32_e32 v2, v132
	v_fmac_f32_e32 v100, v51, v51
	v_mul_f32_e32 v3, s2, v3
	v_mul_f32_e32 v4, v8, v3
	v_fma_f32 v84, v120, v2, -v4
	v_mul_f32_e32 v4, v72, v3
	v_fma_f32 v55, v104, v2, -v4
	v_mul_f32_e32 v4, v40, v3
	v_mul_f32_e32 v3, v24, v3
	v_fma_f32 v40, v56, v2, -v3
	v_rcp_f32_e32 v3, v5
	v_fma_f32 v71, v88, v2, -v4
	v_rcp_f32_e32 v2, v133
	v_fmac_f32_e32 v100, v36, v36
	v_mul_f32_e32 v3, s2, v3
	v_mul_f32_e32 v4, v9, v3
	v_fma_f32 v85, v121, v2, -v4
	v_mul_f32_e32 v4, v73, v3
	v_fma_f32 v56, v105, v2, -v4
	v_mul_f32_e32 v4, v41, v3
	v_mul_f32_e32 v3, v25, v3
	v_fma_f32 v72, v89, v2, -v4
	v_fma_f32 v41, v57, v2, -v3
	ds_read_b128 v[2:5], v139 offset:320
	ds_read_b128 v[6:9], v139 offset:448
	v_fmac_f32_e32 v100, v35, v35
	v_mul_f32_e32 v99, v20, v20
	v_fmac_f32_e32 v99, v34, v34
	s_waitcnt lgkmcnt(1)
	v_rcp_f32_e32 v2, v2
	s_waitcnt lgkmcnt(0)
	v_rcp_f32_e32 v6, v6
	v_fmac_f32_e32 v99, v19, v19
	v_fmac_f32_e32 v99, v18, v18
	v_mul_f32_e32 v116, v52, v52
	v_mul_f32_e32 v6, s2, v6
	v_mul_f32_e32 v10, v10, v6
	v_fma_f32 v86, v122, v2, -v10
	v_mul_f32_e32 v10, v74, v6
	v_fma_f32 v73, v106, v2, -v10
	v_mul_f32_e32 v10, v42, v6
	v_mul_f32_e32 v6, v26, v6
	v_fma_f32 v57, v90, v2, -v10
	v_fma_f32 v42, v58, v2, -v6
	v_rcp_f32_e32 v2, v3
	v_rcp_f32_e32 v3, v7
	v_fmac_f32_e32 v116, v68, v68
	v_fmac_f32_e32 v116, v53, v53
	v_fmac_f32_e32 v116, v37, v37
	v_mul_f32_e32 v3, s2, v3
	v_mul_f32_e32 v6, v11, v3
	v_fma_f32 v39, v123, v2, -v6
	v_mul_f32_e32 v6, v75, v3
	v_fma_f32 v38, v107, v2, -v6
	v_mul_f32_e32 v6, v43, v3
	v_mul_f32_e32 v3, v27, v3
	v_fma_f32 v25, v59, v2, -v3
	v_rcp_f32_e32 v3, v8
	v_fma_f32 v26, v91, v2, -v6
	v_rcp_f32_e32 v2, v4
	v_mul_f32_e32 v102, v69, v69
	v_mul_f32_e32 v3, s2, v3
	v_mul_f32_e32 v4, v12, v3
	v_fma_f32 v24, v124, v2, -v4
	v_mul_f32_e32 v4, v76, v3
	v_fma_f32 v23, v108, v2, -v4
	v_mul_f32_e32 v4, v44, v3
	v_mul_f32_e32 v3, v28, v3
	v_fma_f32 v21, v60, v2, -v3
	v_rcp_f32_e32 v3, v9
	v_fma_f32 v22, v92, v2, -v4
	v_rcp_f32_e32 v2, v5
	ds_read_b128 v[6:9], v139 offset:480
	v_mul_f32_e32 v3, s2, v3
	v_mul_f32_e32 v4, v13, v3
	v_fma_f32 v13, v125, v2, -v4
	v_mul_f32_e32 v4, v77, v3
	v_fma_f32 v12, v109, v2, -v4
	v_mul_f32_e32 v4, v45, v3
	v_mul_f32_e32 v3, v29, v3
	v_fma_f32 v11, v93, v2, -v4
	v_fma_f32 v10, v61, v2, -v3
	ds_read_b128 v[2:5], v139 offset:352
	s_waitcnt lgkmcnt(1)
	v_rcp_f32_e32 v6, v6
	v_fmac_f32_e32 v102, v83, v83
	v_fmac_f32_e32 v102, v70, v70
	v_fmac_f32_e32 v102, v54, v54
	s_waitcnt lgkmcnt(0)
	v_rcp_f32_e32 v2, v2
	v_mul_f32_e32 v6, s2, v6
	v_mul_f32_e32 v14, v14, v6
	v_mul_f32_e32 v27, v46, v6
	v_fma_f32 v28, v126, v2, -v14
	v_mul_f32_e32 v14, v78, v6
	v_mul_f32_e32 v6, v30, v6
	v_fma_f32 v14, v110, v2, -v14
	v_fma_f32 v27, v94, v2, -v27
	v_fma_f32 v6, v62, v2, -v6
	v_rcp_f32_e32 v2, v3
	v_rcp_f32_e32 v3, v7
	v_mul_f32_e32 v101, v55, v55
	v_fmac_f32_e32 v101, v84, v84
	v_fmac_f32_e32 v101, v71, v71
	v_mul_f32_e32 v7, s2, v3
	v_mul_f32_e32 v3, v15, v7
	v_fma_f32 v30, v127, v2, -v3
	v_mul_f32_e32 v3, v79, v7
	v_mul_f32_e32 v29, v47, v7
	v_mul_f32_e32 v7, v31, v7
	v_fma_f32 v15, v111, v2, -v3
	v_fma_f32 v29, v95, v2, -v29
	v_fma_f32 v7, v63, v2, -v7
	v_rcp_f32_e32 v2, v4
	v_rcp_f32_e32 v4, v8
	v_fmac_f32_e32 v101, v40, v40
	v_mul_f32_e32 v87, v56, v56
	v_fmac_f32_e32 v87, v85, v85
	v_mul_f32_e32 v4, s2, v4
	v_mul_f32_e32 v8, v16, v4
	v_fma_f32 v31, v128, v2, -v8
	v_mul_f32_e32 v8, v80, v4
	v_mul_f32_e32 v16, v48, v4
	v_mul_f32_e32 v4, v32, v4
	v_fma_f32 v8, v112, v2, -v8
	v_fma_f32 v16, v96, v2, -v16
	v_fma_f32 v4, v64, v2, -v4
	v_rcp_f32_e32 v2, v5
	v_rcp_f32_e32 v5, v9
	v_fmac_f32_e32 v87, v72, v72
	v_fmac_f32_e32 v87, v41, v41
	v_mul_f32_e32 v74, v73, v73
	v_mul_f32_e32 v5, s2, v5
	v_mul_f32_e32 v9, v17, v5
	v_fma_f32 v32, v129, v2, -v9
	v_mul_f32_e32 v9, v81, v5
	v_fma_f32 v17, v113, v2, -v9
	v_mul_f32_e32 v9, v49, v5
	v_mul_f32_e32 v5, v33, v5
	v_fma_f32 v9, v97, v2, -v9
	v_fma_f32 v5, v65, v2, -v5
	v_fmac_f32_e32 v74, v86, v86
	v_fmac_f32_e32 v74, v57, v57
	v_fmac_f32_e32 v74, v42, v42
	v_mul_f32_e32 v58, v38, v38
	s_nop 1
	v_add_f32_dpp v2, v138, v138 quad_perm:[1,0,3,2] row_mask:0xf bank_mask:0xf
	v_fmac_f32_e32 v58, v39, v39
	v_fmac_f32_e32 v58, v26, v26
	v_fmac_f32_e32 v58, v25, v25
	v_mul_f32_e32 v43, v23, v23
	s_nop 1
	v_add_f32_dpp v2, v2, v2 quad_perm:[2,3,0,1] row_mask:0xf bank_mask:0xf
	v_fmac_f32_e32 v43, v24, v24
	v_fmac_f32_e32 v43, v22, v22
	v_fmac_f32_e32 v43, v21, v21
	v_mul_f32_e32 v44, v12, v12
	s_nop 1
	v_add_f32_dpp v2, v2, v2 row_half_mirror row_mask:0xf bank_mask:0xf
	v_fmac_f32_e32 v44, v13, v13
	v_fmac_f32_e32 v44, v11, v11
	v_fmac_f32_e32 v44, v10, v10
	v_mul_f32_e32 v75, v14, v14
	s_nop 1
	v_add_f32_dpp v2, v2, v2 row_mirror row_mask:0xf bank_mask:0xf
	ds_swizzle_b32 v33, v2 offset:swizzle(SWAP,16)
	v_fmac_f32_e32 v75, v28, v28
	v_fmac_f32_e32 v75, v27, v27
	v_fmac_f32_e32 v75, v6, v6
	v_mul_f32_e32 v3, v15, v15
	s_waitcnt lgkmcnt(0)
	v_add_f32_e32 v2, v2, v33
	v_fmac_f32_e32 v3, v30, v30
	v_fmac_f32_e32 v3, v29, v29
	v_fmac_f32_e32 v3, v7, v7
	v_mul_f32_e32 v76, v8, v8
	s_nop 1
	v_add_f32_dpp v33, v115, v115 quad_perm:[1,0,3,2] row_mask:0xf bank_mask:0xf
	v_fmac_f32_e32 v76, v31, v31
	v_fmac_f32_e32 v76, v16, v16
	v_fmac_f32_e32 v76, v4, v4
	s_mov_b32 s2, s37
	s_nop 1
	v_add_f32_dpp v33, v33, v33 quad_perm:[2,3,0,1] row_mask:0xf bank_mask:0xf
	s_cmp_eq_u32 s2, 0
	v_readlane_b32 s2, v255, 26
	v_readlane_b32 s3, v255, 27
	s_nop 1
	v_add_f32_dpp v33, v33, v33 row_half_mirror row_mask:0xf bank_mask:0xf
	v_mul_f32_e32 v77, v17, v17
	v_fmac_f32_e32 v77, v32, v32
	v_fmac_f32_e32 v77, v9, v9
	v_fmac_f32_e32 v77, v5, v5
	s_nop 1
	v_add_f32_dpp v33, v33, v33 row_mirror row_mask:0xf bank_mask:0xf
	ds_swizzle_b32 v45, v33 offset:swizzle(SWAP,16)
	v_fmamk_f32 v2, v2, 0x3c000000, v244
	s_cselect_b64 vcc, -1, 0
	v_lshl_add_u32 v78, v134, 2, s0
	v_ashrrev_i32_e32 v79, 31, v78
	s_waitcnt lgkmcnt(0)
	v_add_f32_e32 v33, v33, v45
	s_lshl_b32 s36, s1, 1
	v_fmamk_f32 v33, v33, 0x3c000000, v244
	v_rsq_f32_e32 v33, v33
	s_mov_b64 s[0:1], 0x4000
	s_nop 1
	v_add_f32_dpp v45, v100, v100 quad_perm:[1,0,3,2] row_mask:0xf bank_mask:0xf
	v_mul_f32_e32 v67, v67, v33
	s_nop 1
	v_add_f32_dpp v45, v45, v45 quad_perm:[2,3,0,1] row_mask:0xf bank_mask:0xf
	s_nop 1
	v_add_f32_dpp v45, v45, v45 row_half_mirror row_mask:0xf bank_mask:0xf
	s_nop 1
	v_add_f32_dpp v45, v45, v45 row_mirror row_mask:0xf bank_mask:0xf
	ds_swizzle_b32 v46, v45 offset:swizzle(SWAP,16)
	s_waitcnt lgkmcnt(0)
	v_add_f32_e32 v45, v45, v46
	s_nop 1
	v_add_f32_dpp v46, v99, v99 quad_perm:[1,0,3,2] row_mask:0xf bank_mask:0xf
	s_nop 1
	v_add_f32_dpp v46, v46, v46 quad_perm:[2,3,0,1] row_mask:0xf bank_mask:0xf
	s_nop 1
	v_add_f32_dpp v46, v46, v46 row_half_mirror row_mask:0xf bank_mask:0xf
	s_nop 1
	v_add_f32_dpp v46, v46, v46 row_mirror row_mask:0xf bank_mask:0xf
	ds_swizzle_b32 v47, v46 offset:swizzle(SWAP,16)
	s_waitcnt lgkmcnt(0)
	v_add_f32_e32 v46, v46, v47
	s_nop 1
	v_add_f32_dpp v47, v116, v116 quad_perm:[1,0,3,2] row_mask:0xf bank_mask:0xf
	s_nop 1
	v_add_f32_dpp v47, v47, v47 quad_perm:[2,3,0,1] row_mask:0xf bank_mask:0xf
	s_nop 1
	v_add_f32_dpp v47, v47, v47 row_half_mirror row_mask:0xf bank_mask:0xf
	s_nop 1
	v_add_f32_dpp v47, v47, v47 row_mirror row_mask:0xf bank_mask:0xf
	ds_swizzle_b32 v48, v47 offset:swizzle(SWAP,16)
	s_waitcnt lgkmcnt(0)
	v_add_f32_e32 v47, v47, v48
	s_nop 1
	v_add_f32_dpp v48, v102, v102 quad_perm:[1,0,3,2] row_mask:0xf bank_mask:0xf
	s_nop 1
	v_add_f32_dpp v48, v48, v48 quad_perm:[2,3,0,1] row_mask:0xf bank_mask:0xf
	s_nop 1
	v_add_f32_dpp v48, v48, v48 row_half_mirror row_mask:0xf bank_mask:0xf
	s_nop 1
	v_add_f32_dpp v48, v48, v48 row_mirror row_mask:0xf bank_mask:0xf
	ds_swizzle_b32 v49, v48 offset:swizzle(SWAP,16)
	s_waitcnt lgkmcnt(0)
	v_add_f32_e32 v49, v48, v49
	s_nop 1
	v_add_f32_dpp v48, v101, v101 quad_perm:[1,0,3,2] row_mask:0xf bank_mask:0xf
	s_nop 1
	v_add_f32_dpp v48, v48, v48 quad_perm:[2,3,0,1] row_mask:0xf bank_mask:0xf
	s_nop 1
	v_add_f32_dpp v48, v48, v48 row_half_mirror row_mask:0xf bank_mask:0xf
	s_nop 1
	v_add_f32_dpp v48, v48, v48 row_mirror row_mask:0xf bank_mask:0xf
	ds_swizzle_b32 v59, v48 offset:swizzle(SWAP,16)
	s_waitcnt lgkmcnt(0)
	v_add_f32_e32 v59, v48, v59
	s_nop 1
	v_add_f32_dpp v48, v87, v87 quad_perm:[1,0,3,2] row_mask:0xf bank_mask:0xf
	s_nop 1
	v_add_f32_dpp v48, v48, v48 quad_perm:[2,3,0,1] row_mask:0xf bank_mask:0xf
	s_nop 1
	v_add_f32_dpp v48, v48, v48 row_half_mirror row_mask:0xf bank_mask:0xf
	s_nop 1
	v_add_f32_dpp v48, v48, v48 row_mirror row_mask:0xf bank_mask:0xf
	ds_swizzle_b32 v60, v48 offset:swizzle(SWAP,16)
	s_waitcnt lgkmcnt(0)
	v_add_f32_e32 v61, v48, v60
	s_nop 1
	v_add_f32_dpp v48, v74, v74 quad_perm:[1,0,3,2] row_mask:0xf bank_mask:0xf
	s_nop 1
	v_add_f32_dpp v48, v48, v48 quad_perm:[2,3,0,1] row_mask:0xf bank_mask:0xf
	s_nop 1
	v_add_f32_dpp v48, v48, v48 row_half_mirror row_mask:0xf bank_mask:0xf
	s_nop 1
	v_add_f32_dpp v48, v48, v48 row_mirror row_mask:0xf bank_mask:0xf
	ds_swizzle_b32 v60, v48 offset:swizzle(SWAP,16)
	s_waitcnt lgkmcnt(0)
	v_add_f32_e32 v63, v48, v60
	s_nop 1
	v_add_f32_dpp v48, v58, v58 quad_perm:[1,0,3,2] row_mask:0xf bank_mask:0xf
	s_nop 1
	v_add_f32_dpp v48, v48, v48 quad_perm:[2,3,0,1] row_mask:0xf bank_mask:0xf
	s_nop 1
	v_add_f32_dpp v48, v48, v48 row_half_mirror row_mask:0xf bank_mask:0xf
	s_nop 1
	v_add_f32_dpp v48, v48, v48 row_mirror row_mask:0xf bank_mask:0xf
	ds_swizzle_b32 v58, v48 offset:swizzle(SWAP,16)
	s_waitcnt lgkmcnt(0)
	v_add_f32_e32 v64, v48, v58
	s_nop 1
	v_add_f32_dpp v43, v43, v43 quad_perm:[1,0,3,2] row_mask:0xf bank_mask:0xf
	s_nop 1
	v_add_f32_dpp v43, v43, v43 quad_perm:[2,3,0,1] row_mask:0xf bank_mask:0xf
	s_nop 1
	v_add_f32_dpp v43, v43, v43 row_half_mirror row_mask:0xf bank_mask:0xf
	s_nop 1
	v_add_f32_dpp v43, v43, v43 row_mirror row_mask:0xf bank_mask:0xf
	ds_swizzle_b32 v48, v43 offset:swizzle(SWAP,16)
	s_waitcnt lgkmcnt(0)
	v_add_f32_e32 v62, v43, v48
	s_nop 1
	v_add_f32_dpp v43, v44, v44 quad_perm:[1,0,3,2] row_mask:0xf bank_mask:0xf
	s_nop 1
	v_add_f32_dpp v43, v43, v43 quad_perm:[2,3,0,1] row_mask:0xf bank_mask:0xf
	s_nop 1
	v_add_f32_dpp v43, v43, v43 row_half_mirror row_mask:0xf bank_mask:0xf
	s_nop 1
	v_add_f32_dpp v43, v43, v43 row_mirror row_mask:0xf bank_mask:0xf
	ds_swizzle_b32 v44, v43 offset:swizzle(SWAP,16)
	s_waitcnt lgkmcnt(0)
	v_add_f32_e32 v60, v43, v44
	s_nop 1
	v_add_f32_dpp v43, v75, v75 quad_perm:[1,0,3,2] row_mask:0xf bank_mask:0xf
	s_nop 1
	v_add_f32_dpp v43, v43, v43 quad_perm:[2,3,0,1] row_mask:0xf bank_mask:0xf
	s_nop 1
	v_add_f32_dpp v43, v43, v43 row_half_mirror row_mask:0xf bank_mask:0xf
	s_nop 1
	v_add_f32_dpp v43, v43, v43 row_mirror row_mask:0xf bank_mask:0xf
	ds_swizzle_b32 v44, v43 offset:swizzle(SWAP,16)
	s_waitcnt lgkmcnt(0)
	v_add_f32_e32 v58, v43, v44
	s_nop 1
	v_add_f32_dpp v3, v3, v3 quad_perm:[1,0,3,2] row_mask:0xf bank_mask:0xf
	s_nop 1
	v_add_f32_dpp v3, v3, v3 quad_perm:[2,3,0,1] row_mask:0xf bank_mask:0xf
	s_nop 1
	v_add_f32_dpp v3, v3, v3 row_half_mirror row_mask:0xf bank_mask:0xf
	s_nop 1
	v_add_f32_dpp v3, v3, v3 row_mirror row_mask:0xf bank_mask:0xf
	ds_swizzle_b32 v43, v3 offset:swizzle(SWAP,16)
	s_waitcnt lgkmcnt(0)
	v_add_f32_e32 v48, v3, v43
	s_nop 1
	v_add_f32_dpp v3, v76, v76 quad_perm:[1,0,3,2] row_mask:0xf bank_mask:0xf
	v_lshlrev_b32_e32 v76, 2, v0
	global_load_dword v65, v76, s[2:3]
	global_load_dword v74, v76, s[2:3] offset:128
	global_load_dword v75, v76, s[2:3] offset:256
	global_load_dword v76, v76, s[2:3] offset:384
	v_readlane_b32 s2, v254, 63
	v_readlane_b32 s3, v255, 0
	v_lshlrev_b32_e32 v0, 1, v0
	s_nop 1
	v_add_f32_dpp v3, v3, v3 quad_perm:[2,3,0,1] row_mask:0xf bank_mask:0xf
	s_nop 1
	v_add_f32_dpp v3, v3, v3 row_half_mirror row_mask:0xf bank_mask:0xf
	s_nop 1
	v_add_f32_dpp v3, v3, v3 row_mirror row_mask:0xf bank_mask:0xf
	ds_swizzle_b32 v43, v3 offset:swizzle(SWAP,16)
	s_waitcnt lgkmcnt(0)
	v_add_f32_e32 v44, v3, v43
	s_nop 1
	v_add_f32_dpp v3, v77, v77 quad_perm:[1,0,3,2] row_mask:0xf bank_mask:0xf
	v_rsq_f32_e32 v77, v2
	s_nop 1
	v_add_f32_dpp v3, v3, v3 quad_perm:[2,3,0,1] row_mask:0xf bank_mask:0xf
	s_nop 1
	v_add_f32_dpp v3, v3, v3 row_half_mirror row_mask:0xf bank_mask:0xf
	s_nop 1
	v_add_f32_dpp v3, v3, v3 row_mirror row_mask:0xf bank_mask:0xf
	ds_swizzle_b32 v43, v3 offset:swizzle(SWAP,16)
	s_waitcnt lgkmcnt(0)
	v_add_f32_e32 v43, v3, v43
	v_cndmask_b32_e32 v3, v252, v246, vcc
	s_waitcnt vmcnt(3)
	v_mul_f32_e32 v65, v65, v3
	s_waitcnt vmcnt(2)
	v_mul_f32_e32 v74, v3, v74
	s_waitcnt vmcnt(1)
	v_mul_f32_e32 v75, v3, v75
	v_mul_f32_e32 v67, v67, v75
	s_waitcnt vmcnt(0)
	v_mul_f32_e32 v76, v3, v76
	v_lshlrev_b64 v[2:3], 11, v[78:79]
	v_mul_f32_e32 v79, v137, v77
	v_lshl_add_u64 v[2:3], s[2:3], 0, v[2:3]
	v_mul_f32_e32 v79, v79, v65
	v_lshl_add_u64 v[2:3], v[2:3], 0, s[36:37]
	v_bfe_u32 v80, v79, 16, 1
	v_lshl_add_u64 v[2:3], v[2:3], 0, v[0:1]
	v_add3_u32 v79, v79, v80, s86
	global_store_short_d16_hi v[2:3], v79, off offset:1024
	v_mul_f32_e32 v79, v136, v77
	v_mul_f32_e32 v79, v79, v74
	v_bfe_u32 v80, v79, 16, 1
	v_add3_u32 v79, v79, v80, s86
	global_store_short_d16_hi v[2:3], v79, off offset:1088
	v_mul_f32_e32 v79, v135, v77
	v_mul_f32_e32 v79, v79, v75
	v_bfe_u32 v80, v79, 16, 1
	v_mul_f32_e32 v77, v114, v77
	v_add3_u32 v79, v79, v80, s86
	v_mul_f32_e32 v77, v77, v76
	global_store_short_d16_hi v[2:3], v79, off offset:1152
	v_bfe_u32 v79, v77, 16, 1
	v_or_b32_e32 v80, 1, v78
	v_add3_u32 v77, v77, v79, s86
	v_ashrrev_i32_e32 v81, 31, v80
	global_store_short_d16_hi v[2:3], v77, off offset:1216
	v_lshlrev_b64 v[80:81], 11, v[80:81]
	v_mul_f32_e32 v77, v98, v33
	v_lshl_add_u64 v[80:81], s[2:3], 0, v[80:81]
	v_mul_f32_e32 v77, v77, v65
	v_lshl_add_u64 v[80:81], v[80:81], 0, s[36:37]
	v_bfe_u32 v79, v77, 16, 1
	v_lshl_add_u64 v[80:81], v[80:81], 0, v[0:1]
	v_add3_u32 v77, v77, v79, s86
	global_store_short_d16_hi v[80:81], v77, off offset:1024
	v_mul_f32_e32 v77, v82, v33
	v_mul_f32_e32 v33, v66, v33
	v_mul_f32_e32 v33, v33, v76
	v_bfe_u32 v66, v33, 16, 1
	v_mul_f32_e32 v77, v77, v74
	v_add3_u32 v33, v33, v66, s86
	v_bfe_u32 v79, v77, 16, 1
	global_store_short_d16_hi v[80:81], v33, off offset:1216
	v_fmamk_f32 v33, v45, 0x3c000000, v244
	v_add3_u32 v77, v77, v79, s86
	v_rsq_f32_e32 v33, v33
	global_store_short_d16_hi v[80:81], v77, off offset:1088
	v_bfe_u32 v77, v67, 16, 1
	v_add3_u32 v67, v67, v77, s86
	v_or_b32_e32 v66, 2, v78
	global_store_short_d16_hi v[80:81], v67, off offset:1152
	v_ashrrev_i32_e32 v67, 31, v66
	v_lshlrev_b64 v[66:67], 11, v[66:67]
	v_mul_f32_e32 v45, v51, v33
	v_lshl_add_u64 v[66:67], s[2:3], 0, v[66:67]
	v_mul_f32_e32 v45, v45, v65
	v_lshl_add_u64 v[66:67], v[66:67], 0, s[36:37]
	v_bfe_u32 v51, v45, 16, 1
	v_lshl_add_u64 v[66:67], v[66:67], 0, v[0:1]
	v_add3_u32 v45, v45, v51, s86
	global_store_short_d16_hi v[66:67], v45, off offset:1024
	v_mul_f32_e32 v45, v50, v33
	v_mul_f32_e32 v36, v36, v33
	v_mul_f32_e32 v33, v35, v33
	v_mul_f32_e32 v33, v33, v76
	v_mul_f32_e32 v45, v45, v74
	v_bfe_u32 v35, v33, 16, 1
	v_bfe_u32 v50, v45, 16, 1
	v_add3_u32 v33, v33, v35, s86
	v_add3_u32 v45, v45, v50, s86
	global_store_short_d16_hi v[66:67], v33, off offset:1216
	v_fmamk_f32 v33, v46, 0x3c000000, v244
	v_or_b32_e32 v50, 3, v78
	v_rsq_f32_e32 v33, v33
	v_ashrrev_i32_e32 v51, 31, v50
	v_lshlrev_b64 v[50:51], 11, v[50:51]
	v_lshl_add_u64 v[50:51], s[2:3], 0, v[50:51]
	v_lshl_add_u64 v[50:51], v[50:51], 0, s[36:37]
	v_lshl_add_u64 v[50:51], v[50:51], 0, v[0:1]
	v_mul_f32_e32 v0, v34, v33
	v_mul_f32_e32 v0, v0, v65
	v_bfe_u32 v34, v0, 16, 1
	v_add3_u32 v0, v0, v34, s86
	global_store_short_d16_hi v[50:51], v0, off offset:1024
	v_mul_f32_e32 v0, v20, v33
	v_mul_f32_e32 v0, v0, v74
	v_bfe_u32 v20, v0, 16, 1
	v_add3_u32 v0, v0, v20, s86
	global_store_short_d16_hi v[50:51], v0, off offset:1088
	v_mul_f32_e32 v0, v19, v33
	v_mul_f32_e32 v0, v0, v75
	v_bfe_u32 v19, v0, 16, 1
	v_add3_u32 v0, v0, v19, s86
	global_store_short_d16_hi v[50:51], v0, off offset:1152
	v_mul_f32_e32 v0, v18, v33
	v_mul_f32_e32 v0, v0, v76
	v_bfe_u32 v18, v0, 16, 1
	v_add3_u32 v0, v0, v18, s86
	global_store_short_d16_hi v[50:51], v0, off offset:1216
	v_fmamk_f32 v0, v47, 0x3c000000, v244
	v_rsq_f32_e32 v0, v0
	v_lshl_add_u64 v[18:19], v[2:3], 0, s[0:1]
	s_mov_b64 s[0:1], 0x4800
	v_mul_f32_e32 v36, v36, v75
	v_mul_f32_e32 v20, v68, v0
	v_mul_f32_e32 v20, v20, v65
	v_bfe_u32 v33, v20, 16, 1
	v_add3_u32 v20, v20, v33, s86
	global_store_short_d16_hi v[18:19], v20, off offset:1024
	v_mul_f32_e32 v20, v52, v0
	v_mul_f32_e32 v20, v20, v74
	v_bfe_u32 v33, v20, 16, 1
	v_add3_u32 v20, v20, v33, s86
	global_store_short_d16_hi v[18:19], v20, off offset:1088
	v_mul_f32_e32 v20, v53, v0
	v_mul_f32_e32 v20, v20, v75
	v_bfe_u32 v33, v20, 16, 1
	v_mul_f32_e32 v0, v37, v0
	v_add3_u32 v20, v20, v33, s86
	v_mul_f32_e32 v0, v0, v76
	global_store_short_d16_hi v[18:19], v20, off offset:1152
	v_bfe_u32 v20, v0, 16, 1
	v_add3_u32 v0, v0, v20, s86
	global_store_short_d16_hi v[18:19], v0, off offset:1216
	v_fmamk_f32 v0, v49, 0x3c000000, v244
	v_rsq_f32_e32 v0, v0
	v_lshl_add_u64 v[18:19], v[2:3], 0, s[0:1]
	s_mov_b64 s[0:1], 0x5000
	global_store_short_d16_hi v[66:67], v45, off offset:1088
	v_mul_f32_e32 v20, v83, v0
	v_mul_f32_e32 v20, v20, v65
	v_bfe_u32 v33, v20, 16, 1
	v_add3_u32 v20, v20, v33, s86
	global_store_short_d16_hi v[18:19], v20, off offset:1024
	v_mul_f32_e32 v20, v69, v0
	v_mul_f32_e32 v20, v20, v74
	v_bfe_u32 v33, v20, 16, 1
	v_add3_u32 v20, v20, v33, s86
	global_store_short_d16_hi v[18:19], v20, off offset:1088
	v_mul_f32_e32 v20, v70, v0
	v_mul_f32_e32 v20, v20, v75
	v_bfe_u32 v33, v20, 16, 1
	v_mul_f32_e32 v0, v54, v0
	v_add3_u32 v20, v20, v33, s86
	v_mul_f32_e32 v0, v0, v76
	global_store_short_d16_hi v[18:19], v20, off offset:1152
	v_bfe_u32 v20, v0, 16, 1
	v_add3_u32 v0, v0, v20, s86
	global_store_short_d16_hi v[18:19], v0, off offset:1216
	v_fmamk_f32 v0, v59, 0x3c000000, v244
	v_rsq_f32_e32 v0, v0
	v_lshl_add_u64 v[18:19], v[2:3], 0, s[0:1]
	s_mov_b64 s[0:1], 0x5800
	v_bfe_u32 v45, v36, 16, 1
	v_mul_f32_e32 v20, v84, v0
	v_mul_f32_e32 v20, v20, v65
	v_bfe_u32 v33, v20, 16, 1
	v_add3_u32 v20, v20, v33, s86
	global_store_short_d16_hi v[18:19], v20, off offset:1024
	v_mul_f32_e32 v20, v55, v0
	v_mul_f32_e32 v20, v20, v74
	v_bfe_u32 v33, v20, 16, 1
	v_add3_u32 v20, v20, v33, s86
	global_store_short_d16_hi v[18:19], v20, off offset:1088
	v_mul_f32_e32 v20, v71, v0
	v_mul_f32_e32 v20, v20, v75
	v_bfe_u32 v33, v20, 16, 1
	v_mul_f32_e32 v0, v40, v0
	v_add3_u32 v20, v20, v33, s86
	v_mul_f32_e32 v0, v0, v76
	global_store_short_d16_hi v[18:19], v20, off offset:1152
	v_bfe_u32 v20, v0, 16, 1
	v_add3_u32 v0, v0, v20, s86
	global_store_short_d16_hi v[18:19], v0, off offset:1216
	v_fmamk_f32 v0, v61, 0x3c000000, v244
	v_rsq_f32_e32 v0, v0
	v_lshl_add_u64 v[18:19], v[2:3], 0, s[0:1]
	s_mov_b64 s[0:1], 0x8000
	v_add3_u32 v36, v36, v45, s86
	v_mul_f32_e32 v20, v85, v0
	v_mul_f32_e32 v20, v20, v65
	v_bfe_u32 v33, v20, 16, 1
	v_add3_u32 v20, v20, v33, s86
	global_store_short_d16_hi v[18:19], v20, off offset:1024
	v_mul_f32_e32 v20, v56, v0
	v_mul_f32_e32 v20, v20, v74
	v_bfe_u32 v33, v20, 16, 1
	v_add3_u32 v20, v20, v33, s86
	global_store_short_d16_hi v[18:19], v20, off offset:1088
	v_mul_f32_e32 v20, v72, v0
	v_mul_f32_e32 v20, v20, v75
	v_bfe_u32 v33, v20, 16, 1
	v_mul_f32_e32 v0, v41, v0
	v_add3_u32 v20, v20, v33, s86
	v_mul_f32_e32 v0, v0, v76
	global_store_short_d16_hi v[18:19], v20, off offset:1152
	v_bfe_u32 v20, v0, 16, 1
	v_add3_u32 v0, v0, v20, s86
	global_store_short_d16_hi v[18:19], v0, off offset:1216
	v_fmamk_f32 v0, v63, 0x3c000000, v244
	v_rsq_f32_e32 v0, v0
	v_lshl_add_u64 v[18:19], v[2:3], 0, s[0:1]
	s_mov_b64 s[0:1], 0x8800
	global_store_short_d16_hi v[66:67], v36, off offset:1152
	v_mul_f32_e32 v20, v86, v0
	v_mul_f32_e32 v20, v20, v65
	v_bfe_u32 v33, v20, 16, 1
	v_add3_u32 v20, v20, v33, s86
	global_store_short_d16_hi v[18:19], v20, off offset:1024
	v_mul_f32_e32 v20, v73, v0
	v_mul_f32_e32 v20, v20, v74
	v_bfe_u32 v33, v20, 16, 1
	v_add3_u32 v20, v20, v33, s86
	global_store_short_d16_hi v[18:19], v20, off offset:1088
	v_mul_f32_e32 v20, v57, v0
	v_mul_f32_e32 v20, v20, v75
	v_bfe_u32 v33, v20, 16, 1
	v_mul_f32_e32 v0, v42, v0
	v_add3_u32 v20, v20, v33, s86
	v_mul_f32_e32 v0, v0, v76
	global_store_short_d16_hi v[18:19], v20, off offset:1152
	v_bfe_u32 v20, v0, 16, 1
	v_add3_u32 v0, v0, v20, s86
	global_store_short_d16_hi v[18:19], v0, off offset:1216
	v_fmamk_f32 v0, v64, 0x3c000000, v244
	v_rsq_f32_e32 v0, v0
	v_lshl_add_u64 v[18:19], v[2:3], 0, s[0:1]
	s_mov_b64 s[0:1], 0x9000
	v_mul_f32_e32 v20, v39, v0
	v_mul_f32_e32 v20, v20, v65
	v_bfe_u32 v33, v20, 16, 1
	v_add3_u32 v20, v20, v33, s86
	global_store_short_d16_hi v[18:19], v20, off offset:1024
	v_mul_f32_e32 v20, v38, v0
	v_mul_f32_e32 v20, v20, v74
	v_bfe_u32 v33, v20, 16, 1
	v_add3_u32 v20, v20, v33, s86
	global_store_short_d16_hi v[18:19], v20, off offset:1088
	v_mul_f32_e32 v20, v26, v0
	v_mul_f32_e32 v20, v20, v75
	v_bfe_u32 v26, v20, 16, 1
	v_mul_f32_e32 v0, v25, v0
	v_add3_u32 v20, v20, v26, s86
	v_mul_f32_e32 v0, v0, v76
	global_store_short_d16_hi v[18:19], v20, off offset:1152
	v_bfe_u32 v20, v0, 16, 1
	v_add3_u32 v0, v0, v20, s86
	global_store_short_d16_hi v[18:19], v0, off offset:1216
	v_fmamk_f32 v0, v62, 0x3c000000, v244
	v_rsq_f32_e32 v0, v0
	v_lshl_add_u64 v[18:19], v[2:3], 0, s[0:1]
	s_mov_b64 s[0:1], 0x9800
	v_mul_f32_e32 v20, v24, v0
	v_mul_f32_e32 v20, v20, v65
	v_bfe_u32 v24, v20, 16, 1
	v_add3_u32 v20, v20, v24, s86
	global_store_short_d16_hi v[18:19], v20, off offset:1024
	v_mul_f32_e32 v20, v23, v0
	v_mul_f32_e32 v20, v20, v74
	v_bfe_u32 v23, v20, 16, 1
	v_add3_u32 v20, v20, v23, s86
	global_store_short_d16_hi v[18:19], v20, off offset:1088
	v_mul_f32_e32 v20, v22, v0
	v_mul_f32_e32 v20, v20, v75
	v_bfe_u32 v22, v20, 16, 1
	v_mul_f32_e32 v0, v21, v0
	v_add3_u32 v20, v20, v22, s86
	v_mul_f32_e32 v0, v0, v76
	global_store_short_d16_hi v[18:19], v20, off offset:1152
	v_bfe_u32 v20, v0, 16, 1
	v_add3_u32 v0, v0, v20, s86
	global_store_short_d16_hi v[18:19], v0, off offset:1216
	v_fmamk_f32 v0, v60, 0x3c000000, v244
	v_rsq_f32_e32 v0, v0
	v_lshl_add_u64 v[18:19], v[2:3], 0, s[0:1]
	s_mov_b64 s[0:1], 0xc000
	v_mul_f32_e32 v13, v13, v0
	v_mul_f32_e32 v12, v12, v0
	v_mul_f32_e32 v11, v11, v0
	v_mul_f32_e32 v0, v10, v0
	v_mul_f32_e32 v0, v0, v76
	v_bfe_u32 v10, v0, 16, 1
	v_mul_f32_e32 v13, v13, v65
	v_add3_u32 v0, v0, v10, s86
	v_bfe_u32 v20, v13, 16, 1
	global_store_short_d16_hi v[18:19], v0, off offset:1216
	v_fmamk_f32 v0, v58, 0x3c000000, v244
	v_add3_u32 v13, v13, v20, s86
	v_mul_f32_e32 v12, v12, v74
	v_rsq_f32_e32 v0, v0
	global_store_short_d16_hi v[18:19], v13, off offset:1024
	v_bfe_u32 v13, v12, 16, 1
	v_add3_u32 v12, v12, v13, s86
	v_mul_f32_e32 v11, v11, v75
	global_store_short_d16_hi v[18:19], v12, off offset:1088
	v_bfe_u32 v12, v11, 16, 1
	v_add3_u32 v11, v11, v12, s86
	v_mul_f32_e32 v12, v28, v0
	v_mul_f32_e32 v12, v12, v65
	v_bfe_u32 v13, v12, 16, 1
	global_store_short_d16_hi v[18:19], v11, off offset:1152
	v_lshl_add_u64 v[10:11], v[2:3], 0, s[0:1]
	v_add3_u32 v12, v12, v13, s86
	global_store_short_d16_hi v[10:11], v12, off offset:1024
	v_mul_f32_e32 v12, v14, v0
	v_mul_f32_e32 v12, v12, v74
	v_bfe_u32 v13, v12, 16, 1
	v_add3_u32 v12, v12, v13, s86
	global_store_short_d16_hi v[10:11], v12, off offset:1088
	v_mul_f32_e32 v12, v27, v0
	v_mul_f32_e32 v0, v6, v0
	v_mul_f32_e32 v0, v0, v76
	v_bfe_u32 v6, v0, 16, 1
	v_add3_u32 v0, v0, v6, s86
	global_store_short_d16_hi v[10:11], v0, off offset:1216
	v_fmamk_f32 v0, v48, 0x3c000000, v244
	v_rsq_f32_e32 v0, v0
	v_mul_f32_e32 v12, v12, v75
	v_bfe_u32 v13, v12, 16, 1
	v_add3_u32 v12, v12, v13, s86
	v_mul_f32_e32 v6, v30, v0
	v_mul_f32_e32 v6, v6, v65
	global_store_short_d16_hi v[10:11], v12, off offset:1152
	s_mov_b64 s[0:1], 0xc800
	v_bfe_u32 v12, v6, 16, 1
	v_lshl_add_u64 v[10:11], v[2:3], 0, s[0:1]
	v_add3_u32 v6, v6, v12, s86
	global_store_short_d16_hi v[10:11], v6, off offset:1024
	v_mul_f32_e32 v6, v15, v0
	v_mul_f32_e32 v6, v6, v74
	v_bfe_u32 v12, v6, 16, 1
	v_add3_u32 v6, v6, v12, s86
	global_store_short_d16_hi v[10:11], v6, off offset:1088
	v_mul_f32_e32 v6, v29, v0
	v_mul_f32_e32 v6, v6, v75
	v_bfe_u32 v12, v6, 16, 1
	v_mul_f32_e32 v0, v7, v0
	v_add3_u32 v6, v6, v12, s86
	v_mul_f32_e32 v0, v0, v76
	global_store_short_d16_hi v[10:11], v6, off offset:1152
	v_bfe_u32 v6, v0, 16, 1
	v_add3_u32 v0, v0, v6, s86
	global_store_short_d16_hi v[10:11], v0, off offset:1216
	v_fmamk_f32 v0, v44, 0x3c000000, v244
	v_rsq_f32_e32 v0, v0
	s_mov_b64 s[0:1], 0xd000
	v_lshl_add_u64 v[6:7], v[2:3], 0, s[0:1]
	s_mov_b64 s[0:1], 0xd800
	v_mul_f32_e32 v10, v31, v0
	v_mul_f32_e32 v10, v10, v65
	v_bfe_u32 v11, v10, 16, 1
	v_mul_f32_e32 v8, v8, v0
	v_add3_u32 v10, v10, v11, s86
	v_mul_f32_e32 v8, v8, v74
	global_store_short_d16_hi v[6:7], v10, off offset:1024
	v_bfe_u32 v10, v8, 16, 1
	v_add3_u32 v8, v8, v10, s86
	global_store_short_d16_hi v[6:7], v8, off offset:1088
	v_mul_f32_e32 v8, v16, v0
	v_mul_f32_e32 v0, v4, v0
	v_mul_f32_e32 v0, v0, v76
	v_bfe_u32 v4, v0, 16, 1
	v_add3_u32 v0, v0, v4, s86
	global_store_short_d16_hi v[6:7], v0, off offset:1216
	v_fmamk_f32 v0, v43, 0x3c000000, v244
	v_rsq_f32_e32 v0, v0
	v_mul_f32_e32 v8, v8, v75
	v_bfe_u32 v10, v8, 16, 1
	v_add3_u32 v8, v8, v10, s86
	v_mul_f32_e32 v4, v32, v0
	v_mul_f32_e32 v4, v65, v4
	global_store_short_d16_hi v[6:7], v8, off offset:1152
	v_bfe_u32 v6, v4, 16, 1
	v_lshl_add_u64 v[2:3], v[2:3], 0, s[0:1]
	v_add3_u32 v4, v4, v6, s86
	global_store_short_d16_hi v[2:3], v4, off offset:1024
	v_mul_f32_e32 v4, v17, v0
	v_mul_f32_e32 v4, v74, v4
	v_bfe_u32 v6, v4, 16, 1
	v_add3_u32 v4, v4, v6, s86
	global_store_short_d16_hi v[2:3], v4, off offset:1088
	v_mul_f32_e32 v4, v9, v0
	v_mul_f32_e32 v4, v75, v4
	v_bfe_u32 v6, v4, 16, 1
	v_mul_f32_e32 v0, v5, v0
	v_add3_u32 v4, v4, v6, s86
	v_mul_f32_e32 v0, v76, v0
	global_store_short_d16_hi v[2:3], v4, off offset:1152
	v_bfe_u32 v4, v0, 16, 1
	v_add3_u32 v0, v0, v4, s86
	global_store_short_d16_hi v[2:3], v0, off offset:1216
	s_waitcnt lgkmcnt(0)
	s_barrier

.LBB0_920:
	s_waitcnt vmcnt(3)
	v_lshlrev_b32_e32 v9, 16, v18
	s_waitcnt vmcnt(1)
	v_lshlrev_b32_e32 v77, 16, v22
	v_lshlrev_b32_e32 v73, 16, v20
	s_waitcnt vmcnt(0)
	v_lshlrev_b32_e32 v81, 16, v24
	v_fmac_f32_e32 v77, v0, v9
	v_add_f32_e32 v9, v77, v81
	v_mul_f32_e32 v77, 0xbfb8aa3b, v73
	v_exp_f32_e32 v77, v77
	v_and_b32_e32 v74, 0xffff0000, v20
	v_lshlrev_b32_e32 v75, 16, v21
	v_lshlrev_b32_e32 v71, 16, v19
	v_add_f32_e32 v77, 1.0, v77
	v_rcp_f32_e32 v77, v77
	v_lshlrev_b32_e32 v79, 16, v23
	v_lshlrev_b32_e32 v83, 16, v25
	v_fmac_f32_e32 v79, v0, v71
	v_mul_f32_e32 v73, v77, v73
	v_mul_f32_e32 v9, v73, v9
	v_mul_f32_e32 v73, 0xbfb8aa3b, v74
	v_exp_f32_e32 v73, v73
	v_and_b32_e32 v76, 0xffff0000, v21
	v_add_f32_e32 v71, v79, v83
	v_and_b32_e32 v70, 0xffff0000, v18
	v_add_f32_e32 v73, 1.0, v73
	v_rcp_f32_e32 v73, v73
	v_and_b32_e32 v78, 0xffff0000, v22
	v_and_b32_e32 v82, 0xffff0000, v24
	v_fmac_f32_e32 v78, v0, v70
	v_mul_f32_e32 v73, v73, v74
	v_mul_f32_e32 v74, 0xbfb8aa3b, v75
	v_exp_f32_e32 v74, v74
	v_add_f32_e32 v70, v78, v82
	v_and_b32_e32 v72, 0xffff0000, v19
	v_and_b32_e32 v80, 0xffff0000, v23
	v_add_f32_e32 v74, 1.0, v74
	v_rcp_f32_e32 v74, v74
	v_mul_f32_e32 v70, v73, v70
	v_and_b32_e32 v84, 0xffff0000, v25
	v_mul_f32_e32 v73, v70, v70
	v_mul_f32_e32 v74, v74, v75
	v_mul_f32_e32 v71, v74, v71
	v_mul_f32_e32 v74, 0xbfb8aa3b, v76
	v_exp_f32_e32 v74, v74
	v_fmac_f32_e32 v80, v0, v72
	v_fmac_f32_e32 v73, v9, v9
	v_add_f32_e32 v72, v80, v84
	v_add_f32_e32 v74, 1.0, v74
	v_rcp_f32_e32 v74, v74
	v_fmac_f32_e32 v73, v71, v71
	s_sub_i32 s56, s44, 24
	s_cmp_ge_i32 s56, s36
	v_mul_f32_e32 v74, v74, v76
	v_mul_f32_e32 v72, v74, v72
	v_fmac_f32_e32 v73, v72, v72
	s_nop 1
	v_add_f32_dpp v73, v73, v73 quad_perm:[1,0,3,2] row_mask:0xf bank_mask:0xf
	s_nop 1
	v_add_f32_dpp v73, v73, v73 quad_perm:[2,3,0,1] row_mask:0xf bank_mask:0xf
	s_nop 1
	v_add_f32_dpp v73, v73, v73 row_half_mirror row_mask:0xf bank_mask:0xf
	s_nop 1
	v_add_f32_dpp v73, v73, v73 row_mirror row_mask:0xf bank_mask:0xf
	ds_swizzle_b32 v74, v73 offset:swizzle(SWAP,16)
	s_waitcnt lgkmcnt(0)
	v_add_f32_e32 v73, v73, v74
	v_fmamk_f32 v73, v73, 0x3c000000, v244
	v_rsq_f32_e32 v73, v73
	s_nop 0
	v_mul_f32_e32 v9, v9, v73
	v_mul_f32_e32 v70, v70, v73
	v_mul_f32_e32 v9, v2, v9
	v_mul_f32_e32 v70, v3, v70
	v_cvt_pk_bf16_f32 v70, v9, v70
	v_mul_f32_e32 v9, v71, v73
	v_mul_f32_e32 v71, v72, v73
	v_mul_f32_e32 v71, v5, v71
	v_lshl_add_u64 v[72:73], s[42:43], 0, v[10:11]
	v_mul_f32_e32 v9, v4, v9
	v_cvt_pk_bf16_f32 v71, v9, v71
	global_store_dwordx2 v[72:73], v[70:71], off
	s_cbranch_scc1 .LBB0_923
	v_lshlrev_b32_e32 v9, 16, v26
	v_lshlrev_b32_e32 v77, 16, v30
	v_lshlrev_b32_e32 v73, 16, v28
	v_lshlrev_b32_e32 v81, 16, v32
	v_fmac_f32_e32 v77, v0, v9
	v_add_f32_e32 v9, v77, v81
	v_mul_f32_e32 v77, 0xbfb8aa3b, v73
	v_exp_f32_e32 v77, v77
	v_and_b32_e32 v74, 0xffff0000, v28
	v_lshlrev_b32_e32 v75, 16, v29
	v_lshlrev_b32_e32 v71, 16, v27
	v_add_f32_e32 v77, 1.0, v77
	v_rcp_f32_e32 v77, v77
	v_lshlrev_b32_e32 v79, 16, v31
	v_lshlrev_b32_e32 v83, 16, v33
	v_fmac_f32_e32 v79, v0, v71
	v_mul_f32_e32 v73, v77, v73
	v_mul_f32_e32 v9, v73, v9
	v_mul_f32_e32 v73, 0xbfb8aa3b, v74
	v_exp_f32_e32 v73, v73
	v_and_b32_e32 v76, 0xffff0000, v29
	v_add_f32_e32 v71, v79, v83
	v_and_b32_e32 v70, 0xffff0000, v26
	v_add_f32_e32 v73, 1.0, v73
	v_rcp_f32_e32 v73, v73
	v_and_b32_e32 v78, 0xffff0000, v30
	v_and_b32_e32 v82, 0xffff0000, v32
	v_fmac_f32_e32 v78, v0, v70
	v_mul_f32_e32 v73, v73, v74
	v_mul_f32_e32 v74, 0xbfb8aa3b, v75
	v_exp_f32_e32 v74, v74
	v_add_f32_e32 v70, v78, v82
	v_and_b32_e32 v72, 0xffff0000, v27
	v_and_b32_e32 v80, 0xffff0000, v31
	v_add_f32_e32 v74, 1.0, v74
	v_rcp_f32_e32 v74, v74
	v_mul_f32_e32 v70, v73, v70
	v_and_b32_e32 v84, 0xffff0000, v33
	v_mul_f32_e32 v73, v70, v70
	v_mul_f32_e32 v74, v74, v75
	v_mul_f32_e32 v71, v74, v71
	v_mul_f32_e32 v74, 0xbfb8aa3b, v76
	v_exp_f32_e32 v74, v74
	v_fmac_f32_e32 v80, v0, v72
	v_fmac_f32_e32 v73, v9, v9
	v_add_f32_e32 v72, v80, v84
	v_add_f32_e32 v74, 1.0, v74
	v_rcp_f32_e32 v74, v74
	v_fmac_f32_e32 v73, v71, v71
	s_ashr_i32 s57, s56, 31
	s_lshl_b64 s[56:57], s[56:57], 11
	v_mul_f32_e32 v74, v74, v76
	v_mul_f32_e32 v72, v74, v72
	v_fmac_f32_e32 v73, v72, v72
	s_nop 1
	v_add_f32_dpp v73, v73, v73 quad_perm:[1,0,3,2] row_mask:0xf bank_mask:0xf
	s_nop 1
	v_add_f32_dpp v73, v73, v73 quad_perm:[2,3,0,1] row_mask:0xf bank_mask:0xf
	s_nop 1
	v_add_f32_dpp v73, v73, v73 row_half_mirror row_mask:0xf bank_mask:0xf
	s_nop 1
	v_add_f32_dpp v73, v73, v73 row_mirror row_mask:0xf bank_mask:0xf
	ds_swizzle_b32 v74, v73 offset:swizzle(SWAP,16)
	s_waitcnt lgkmcnt(0)
	v_add_f32_e32 v73, v73, v74
	v_fmamk_f32 v73, v73, 0x3c000000, v244
	v_rsq_f32_e32 v73, v73
	s_nop 0
	v_mul_f32_e32 v9, v9, v73
	v_mul_f32_e32 v70, v70, v73
	v_mul_f32_e32 v9, v2, v9
	v_mul_f32_e32 v70, v3, v70
	v_cvt_pk_bf16_f32 v70, v9, v70
	v_mul_f32_e32 v9, v71, v73
	v_mul_f32_e32 v71, v72, v73
	v_mul_f32_e32 v71, v5, v71
	v_lshl_add_u64 v[72:73], v[44:45], 0, s[56:57]
	v_mul_f32_e32 v9, v4, v9
	v_cvt_pk_bf16_f32 v71, v9, v71
	global_store_dwordx2 v[72:73], v[70:71], off offset:512
	s_add_i32 s56, s44, -16
	s_cmp_ge_i32 s56, s36
	s_cbranch_scc0 .LBB0_924

.LBB0_924:
	v_lshlrev_b32_e32 v9, 16, v34
	v_lshlrev_b32_e32 v77, 16, v38
	v_lshlrev_b32_e32 v73, 16, v36
	v_lshlrev_b32_e32 v81, 16, v40
	v_fmac_f32_e32 v77, v0, v9
	v_add_f32_e32 v9, v77, v81
	v_mul_f32_e32 v77, 0xbfb8aa3b, v73
	v_exp_f32_e32 v77, v77
	v_and_b32_e32 v74, 0xffff0000, v36
	v_lshlrev_b32_e32 v75, 16, v37
	v_lshlrev_b32_e32 v71, 16, v35
	v_add_f32_e32 v77, 1.0, v77
	v_rcp_f32_e32 v77, v77
	v_lshlrev_b32_e32 v79, 16, v39
	v_lshlrev_b32_e32 v83, 16, v41
	v_fmac_f32_e32 v79, v0, v71
	v_mul_f32_e32 v73, v77, v73
	v_mul_f32_e32 v9, v73, v9
	v_mul_f32_e32 v73, 0xbfb8aa3b, v74
	v_exp_f32_e32 v73, v73
	v_and_b32_e32 v76, 0xffff0000, v37
	v_add_f32_e32 v71, v79, v83
	v_and_b32_e32 v70, 0xffff0000, v34
	v_add_f32_e32 v73, 1.0, v73
	v_rcp_f32_e32 v73, v73
	v_and_b32_e32 v78, 0xffff0000, v38
	v_and_b32_e32 v82, 0xffff0000, v40
	v_fmac_f32_e32 v78, v0, v70
	v_mul_f32_e32 v73, v73, v74
	v_mul_f32_e32 v74, 0xbfb8aa3b, v75
	v_exp_f32_e32 v74, v74
	v_add_f32_e32 v70, v78, v82
	v_and_b32_e32 v72, 0xffff0000, v35
	v_and_b32_e32 v80, 0xffff0000, v39
	v_add_f32_e32 v74, 1.0, v74
	v_rcp_f32_e32 v74, v74
	v_mul_f32_e32 v70, v73, v70
	v_and_b32_e32 v84, 0xffff0000, v41
	v_mul_f32_e32 v73, v70, v70
	v_mul_f32_e32 v74, v74, v75
	v_mul_f32_e32 v71, v74, v71
	v_mul_f32_e32 v74, 0xbfb8aa3b, v76
	v_exp_f32_e32 v74, v74
	v_fmac_f32_e32 v80, v0, v72
	v_fmac_f32_e32 v73, v9, v9
	v_add_f32_e32 v72, v80, v84
	v_add_f32_e32 v74, 1.0, v74
	v_rcp_f32_e32 v74, v74
	v_fmac_f32_e32 v73, v71, v71
	s_ashr_i32 s57, s56, 31
	s_lshl_b64 s[56:57], s[56:57], 11
	v_mul_f32_e32 v74, v74, v76
	v_mul_f32_e32 v72, v74, v72
	v_fmac_f32_e32 v73, v72, v72
	s_nop 1
	v_add_f32_dpp v73, v73, v73 quad_perm:[1,0,3,2] row_mask:0xf bank_mask:0xf
	s_nop 1
	v_add_f32_dpp v73, v73, v73 quad_perm:[2,3,0,1] row_mask:0xf bank_mask:0xf
	s_nop 1
	v_add_f32_dpp v73, v73, v73 row_half_mirror row_mask:0xf bank_mask:0xf
	s_nop 1
	v_add_f32_dpp v73, v73, v73 row_mirror row_mask:0xf bank_mask:0xf
	ds_swizzle_b32 v74, v73 offset:swizzle(SWAP,16)
	s_waitcnt lgkmcnt(0)
	v_add_f32_e32 v73, v73, v74
	v_fmamk_f32 v73, v73, 0x3c000000, v244
	v_rsq_f32_e32 v73, v73
	s_nop 0
	v_mul_f32_e32 v9, v9, v73
	v_mul_f32_e32 v70, v70, v73
	v_mul_f32_e32 v9, v2, v9
	v_mul_f32_e32 v70, v3, v70
	v_cvt_pk_bf16_f32 v70, v9, v70
	v_mul_f32_e32 v9, v71, v73
	v_mul_f32_e32 v71, v72, v73
	v_mul_f32_e32 v71, v5, v71
	v_lshl_add_u64 v[72:73], v[44:45], 0, s[56:57]
	v_mul_f32_e32 v9, v4, v9
	v_cvt_pk_bf16_f32 v71, v9, v71
	global_store_dwordx2 v[72:73], v[70:71], off offset:512
	s_andn2_b64 vcc, exec, s[54:55]
	s_cbranch_vccnz .LBB0_914

.LBB0_930:
	v_lshlrev_b32_e32 v9, 16, v46
	v_lshlrev_b32_e32 v77, 16, v62
	v_lshlrev_b32_e32 v73, 16, v48
	v_lshlrev_b32_e32 v81, 16, v68
	v_fmac_f32_e32 v77, v0, v9
	v_add_f32_e32 v9, v77, v81
	v_mul_f32_e32 v77, 0xbfb8aa3b, v73
	v_exp_f32_e32 v77, v77
	v_and_b32_e32 v74, 0xffff0000, v48
	v_lshlrev_b32_e32 v75, 16, v49
	v_lshlrev_b32_e32 v71, 16, v47
	v_add_f32_e32 v77, 1.0, v77
	v_rcp_f32_e32 v77, v77
	v_lshlrev_b32_e32 v79, 16, v63
	v_lshlrev_b32_e32 v83, 16, v69
	v_fmac_f32_e32 v79, v0, v71
	v_mul_f32_e32 v73, v77, v73
	v_mul_f32_e32 v9, v73, v9
	v_mul_f32_e32 v73, 0xbfb8aa3b, v74
	v_exp_f32_e32 v73, v73
	v_and_b32_e32 v76, 0xffff0000, v49
	v_add_f32_e32 v71, v79, v83
	v_and_b32_e32 v70, 0xffff0000, v46
	v_add_f32_e32 v73, 1.0, v73
	v_rcp_f32_e32 v73, v73
	v_and_b32_e32 v78, 0xffff0000, v62
	v_and_b32_e32 v82, 0xffff0000, v68
	v_fmac_f32_e32 v78, v0, v70
	v_mul_f32_e32 v73, v73, v74
	v_mul_f32_e32 v74, 0xbfb8aa3b, v75
	v_exp_f32_e32 v74, v74
	v_add_f32_e32 v70, v78, v82
	v_and_b32_e32 v72, 0xffff0000, v47
	v_and_b32_e32 v80, 0xffff0000, v63
	v_add_f32_e32 v74, 1.0, v74
	v_rcp_f32_e32 v74, v74
	v_mul_f32_e32 v70, v73, v70
	v_and_b32_e32 v84, 0xffff0000, v69
	v_mul_f32_e32 v73, v70, v70
	v_mul_f32_e32 v74, v74, v75
	v_mul_f32_e32 v71, v74, v71
	v_mul_f32_e32 v74, 0xbfb8aa3b, v76
	v_exp_f32_e32 v74, v74
	v_fmac_f32_e32 v80, v0, v72
	v_fmac_f32_e32 v73, v9, v9
	v_add_f32_e32 v72, v80, v84
	v_add_f32_e32 v74, 1.0, v74
	v_rcp_f32_e32 v74, v74
	v_fmac_f32_e32 v73, v71, v71
	s_cmp_ge_i32 s44, s36
	v_mul_f32_e32 v74, v74, v76
	v_mul_f32_e32 v72, v74, v72
	v_fmac_f32_e32 v73, v72, v72
	s_nop 1
	v_add_f32_dpp v73, v73, v73 quad_perm:[1,0,3,2] row_mask:0xf bank_mask:0xf
	s_nop 1
	v_add_f32_dpp v73, v73, v73 quad_perm:[2,3,0,1] row_mask:0xf bank_mask:0xf
	s_nop 1
	v_add_f32_dpp v73, v73, v73 row_half_mirror row_mask:0xf bank_mask:0xf
	s_nop 1
	v_add_f32_dpp v73, v73, v73 row_mirror row_mask:0xf bank_mask:0xf
	ds_swizzle_b32 v74, v73 offset:swizzle(SWAP,16)
	s_waitcnt lgkmcnt(0)
	v_add_f32_e32 v73, v73, v74
	v_fmamk_f32 v73, v73, 0x3c000000, v244
	v_rsq_f32_e32 v73, v73
	s_nop 0
	v_mul_f32_e32 v9, v9, v73
	v_mul_f32_e32 v70, v70, v73
	v_mul_f32_e32 v9, v2, v9
	v_mul_f32_e32 v70, v3, v70
	v_cvt_pk_bf16_f32 v70, v9, v70
	v_mul_f32_e32 v9, v71, v73
	v_mul_f32_e32 v71, v72, v73
	v_mul_f32_e32 v71, v5, v71
	v_lshl_add_u64 v[72:73], s[46:47], 0, v[10:11]
	v_mul_f32_e32 v9, v4, v9
	v_cvt_pk_bf16_f32 v71, v9, v71
	global_store_dwordx2 v[72:73], v[70:71], off
	s_cbranch_scc1 .LBB0_932
	v_lshlrev_b32_e32 v9, 16, v50
	v_lshlrev_b32_e32 v77, 16, v58
	v_lshlrev_b32_e32 v73, 16, v54
	v_lshlrev_b32_e32 v81, 16, v64
	v_fmac_f32_e32 v77, v0, v9
	v_add_f32_e32 v9, v77, v81
	v_mul_f32_e32 v77, 0xbfb8aa3b, v73
	v_exp_f32_e32 v77, v77
	v_and_b32_e32 v74, 0xffff0000, v54
	v_lshlrev_b32_e32 v75, 16, v55
	v_lshlrev_b32_e32 v71, 16, v51
	v_add_f32_e32 v77, 1.0, v77
	v_rcp_f32_e32 v77, v77
	v_lshlrev_b32_e32 v79, 16, v59
	v_lshlrev_b32_e32 v83, 16, v65
	v_fmac_f32_e32 v79, v0, v71
	v_mul_f32_e32 v73, v77, v73
	v_mul_f32_e32 v9, v73, v9
	v_mul_f32_e32 v73, 0xbfb8aa3b, v74
	v_exp_f32_e32 v73, v73
	v_and_b32_e32 v76, 0xffff0000, v55
	v_add_f32_e32 v71, v79, v83
	v_and_b32_e32 v70, 0xffff0000, v50
	v_add_f32_e32 v73, 1.0, v73
	v_rcp_f32_e32 v73, v73
	v_and_b32_e32 v78, 0xffff0000, v58
	v_and_b32_e32 v82, 0xffff0000, v64
	v_fmac_f32_e32 v78, v0, v70
	v_mul_f32_e32 v73, v73, v74
	v_mul_f32_e32 v74, 0xbfb8aa3b, v75
	v_exp_f32_e32 v74, v74
	v_add_f32_e32 v70, v78, v82
	v_and_b32_e32 v72, 0xffff0000, v51
	v_and_b32_e32 v80, 0xffff0000, v59
	v_add_f32_e32 v74, 1.0, v74
	v_rcp_f32_e32 v74, v74
	v_mul_f32_e32 v70, v73, v70
	v_and_b32_e32 v84, 0xffff0000, v65
	v_mul_f32_e32 v73, v70, v70
	v_mul_f32_e32 v74, v74, v75
	v_mul_f32_e32 v71, v74, v71
	v_mul_f32_e32 v74, 0xbfb8aa3b, v76
	v_exp_f32_e32 v74, v74
	v_fmac_f32_e32 v80, v0, v72
	v_fmac_f32_e32 v73, v9, v9
	v_add_f32_e32 v72, v80, v84
	v_add_f32_e32 v74, 1.0, v74
	v_rcp_f32_e32 v74, v74
	v_fmac_f32_e32 v73, v71, v71
	s_ashr_i32 s45, s44, 31
	s_lshl_b64 s[54:55], s[44:45], 11
	v_mul_f32_e32 v74, v74, v76
	v_mul_f32_e32 v72, v74, v72
	v_fmac_f32_e32 v73, v72, v72
	s_nop 1
	v_add_f32_dpp v73, v73, v73 quad_perm:[1,0,3,2] row_mask:0xf bank_mask:0xf
	s_nop 1
	v_add_f32_dpp v73, v73, v73 quad_perm:[2,3,0,1] row_mask:0xf bank_mask:0xf
	s_nop 1
	v_add_f32_dpp v73, v73, v73 row_half_mirror row_mask:0xf bank_mask:0xf
	s_nop 1
	v_add_f32_dpp v73, v73, v73 row_mirror row_mask:0xf bank_mask:0xf
	ds_swizzle_b32 v74, v73 offset:swizzle(SWAP,16)
	s_waitcnt lgkmcnt(0)
	v_add_f32_e32 v73, v73, v74
	v_fmamk_f32 v73, v73, 0x3c000000, v244
	v_rsq_f32_e32 v73, v73
	s_nop 0
	v_mul_f32_e32 v9, v9, v73
	v_mul_f32_e32 v70, v70, v73
	v_mul_f32_e32 v9, v2, v9
	v_mul_f32_e32 v70, v3, v70
	v_cvt_pk_bf16_f32 v70, v9, v70
	v_mul_f32_e32 v9, v71, v73
	v_mul_f32_e32 v71, v72, v73
	v_mul_f32_e32 v71, v5, v71
	v_lshl_add_u64 v[72:73], v[44:45], 0, s[54:55]
	v_mul_f32_e32 v9, v4, v9
	v_cvt_pk_bf16_f32 v71, v9, v71
	global_store_dwordx2 v[72:73], v[70:71], off offset:512
.LBB0_932:
	s_add_i32 s54, s44, 8
	s_cmp_ge_i32 s54, s36
	s_cbranch_scc1 .LBB0_914
	v_lshlrev_b32_e32 v9, 16, v52
	v_lshlrev_b32_e32 v77, 16, v60
	v_lshlrev_b32_e32 v73, 16, v56
	v_lshlrev_b32_e32 v81, 16, v66
	v_fmac_f32_e32 v77, v0, v9
	v_add_f32_e32 v9, v77, v81
	v_mul_f32_e32 v77, 0xbfb8aa3b, v73
	v_exp_f32_e32 v77, v77
	v_and_b32_e32 v74, 0xffff0000, v56
	v_lshlrev_b32_e32 v75, 16, v57
	v_lshlrev_b32_e32 v71, 16, v53
	v_add_f32_e32 v77, 1.0, v77
	v_rcp_f32_e32 v77, v77
	v_lshlrev_b32_e32 v79, 16, v61
	v_lshlrev_b32_e32 v83, 16, v67
	v_fmac_f32_e32 v79, v0, v71
	v_mul_f32_e32 v73, v77, v73
	v_mul_f32_e32 v9, v73, v9
	v_mul_f32_e32 v73, 0xbfb8aa3b, v74
	v_exp_f32_e32 v73, v73
	v_and_b32_e32 v76, 0xffff0000, v57
	v_add_f32_e32 v71, v79, v83
	v_and_b32_e32 v70, 0xffff0000, v52
	v_add_f32_e32 v73, 1.0, v73
	v_rcp_f32_e32 v73, v73
	v_and_b32_e32 v78, 0xffff0000, v60
	v_and_b32_e32 v82, 0xffff0000, v66
	v_fmac_f32_e32 v78, v0, v70
	v_mul_f32_e32 v73, v73, v74
	v_mul_f32_e32 v74, 0xbfb8aa3b, v75
	v_exp_f32_e32 v74, v74
	v_add_f32_e32 v70, v78, v82
	v_and_b32_e32 v72, 0xffff0000, v53
	v_and_b32_e32 v80, 0xffff0000, v61
	v_add_f32_e32 v74, 1.0, v74
	v_rcp_f32_e32 v74, v74
	v_mul_f32_e32 v70, v73, v70
	v_and_b32_e32 v84, 0xffff0000, v67
	v_mul_f32_e32 v73, v70, v70
	v_mul_f32_e32 v74, v74, v75
	v_mul_f32_e32 v71, v74, v71
	v_mul_f32_e32 v74, 0xbfb8aa3b, v76
	v_exp_f32_e32 v74, v74
	v_fmac_f32_e32 v80, v0, v72
	v_fmac_f32_e32 v73, v9, v9
	v_add_f32_e32 v72, v80, v84
	v_add_f32_e32 v74, 1.0, v74
	v_rcp_f32_e32 v74, v74
	v_fmac_f32_e32 v73, v71, v71
	s_ashr_i32 s55, s54, 31
	s_lshl_b64 s[54:55], s[54:55], 11
	v_mul_f32_e32 v74, v74, v76
	v_mul_f32_e32 v72, v74, v72
	v_fmac_f32_e32 v73, v72, v72
	s_nop 1
	v_add_f32_dpp v73, v73, v73 quad_perm:[1,0,3,2] row_mask:0xf bank_mask:0xf
	s_nop 1
	v_add_f32_dpp v73, v73, v73 quad_perm:[2,3,0,1] row_mask:0xf bank_mask:0xf
	s_nop 1
	v_add_f32_dpp v73, v73, v73 row_half_mirror row_mask:0xf bank_mask:0xf
	s_nop 1
	v_add_f32_dpp v73, v73, v73 row_mirror row_mask:0xf bank_mask:0xf
	ds_swizzle_b32 v74, v73 offset:swizzle(SWAP,16)
	s_waitcnt lgkmcnt(0)
	v_add_f32_e32 v73, v73, v74
	v_fmamk_f32 v73, v73, 0x3c000000, v244
	v_rsq_f32_e32 v73, v73
	s_nop 0
	v_mul_f32_e32 v9, v9, v73
	v_mul_f32_e32 v70, v70, v73
	v_mul_f32_e32 v9, v2, v9
	v_mul_f32_e32 v70, v3, v70
	v_cvt_pk_bf16_f32 v70, v9, v70
	v_mul_f32_e32 v9, v71, v73
	v_mul_f32_e32 v71, v72, v73
	v_mul_f32_e32 v71, v5, v71
	v_lshl_add_u64 v[72:73], v[44:45], 0, s[54:55]
	v_mul_f32_e32 v9, v4, v9
	v_cvt_pk_bf16_f32 v71, v9, v71
	global_store_dwordx2 v[72:73], v[70:71], off offset:512
	s_branch .LBB0_914

.LBB0_942:
	v_ashrrev_i32_e32 v9, 31, v8
	s_waitcnt lgkmcnt(0)
	v_lshl_add_u64 v[2:3], v[8:9], 2, s[8:9]
	global_load_dword v0, v[2:3], off
	v_lshl_add_u64 v[2:3], v[6:7], 2, s[10:11]
	global_load_dwordx4 v[2:5], v[2:3], off
	s_and_b64 vcc, exec, s[6:7]
	s_cbranch_vccnz .LBB0_944
	s_waitcnt vmcnt(5)
	v_and_b32_e32 v9, 0xffff0000, v32
	s_waitcnt vmcnt(3)
	v_lshlrev_b32_e32 v36, 16, v30
	v_and_b32_e32 v30, 0xffff0000, v30
	v_lshlrev_b32_e32 v34, 16, v26
	v_and_b32_e32 v26, 0xffff0000, v26
	v_lshlrev_b32_e32 v35, 16, v27
	s_waitcnt vmcnt(2)
	v_lshlrev_b32_e32 v38, 16, v28
	v_and_b32_e32 v28, 0xffff0000, v28
	s_waitcnt vmcnt(1)
	v_fmac_f32_e32 v30, v0, v9
	v_add_f32_e32 v9, v30, v28
	v_mul_f32_e32 v28, 0xbfb8aa3b, v26
	v_mul_f32_e32 v30, 0xbfb8aa3b, v35
	v_exp_f32_e32 v28, v28
	v_exp_f32_e32 v30, v30
	v_lshlrev_b32_e32 v8, 16, v32
	v_lshlrev_b32_e32 v32, 16, v33
	v_add_f32_e32 v28, 1.0, v28
	v_add_f32_e32 v30, 1.0, v30
	v_rcp_f32_e32 v28, v28
	v_rcp_f32_e32 v30, v30
	v_lshlrev_b32_e32 v37, 16, v31
	v_fmac_f32_e32 v36, v0, v8
	v_lshlrev_b32_e32 v39, 16, v29
	v_add_f32_e32 v8, v36, v38
	v_mul_f32_e32 v36, 0xbfb8aa3b, v34
	v_fmac_f32_e32 v37, v0, v32
	v_and_b32_e32 v27, 0xffff0000, v27
	v_exp_f32_e32 v36, v36
	v_mul_f32_e32 v26, v28, v26
	v_add_f32_e32 v28, v37, v39
	v_mul_f32_e32 v30, v30, v35
	v_mul_f32_e32 v28, v28, v30
	v_mul_f32_e32 v30, 0xbfb8aa3b, v27
	v_exp_f32_e32 v30, v30
	v_add_f32_e32 v36, 1.0, v36
	v_rcp_f32_e32 v36, v36
	v_and_b32_e32 v33, 0xffff0000, v33
	v_add_f32_e32 v30, 1.0, v30
	v_rcp_f32_e32 v30, v30
	v_and_b32_e32 v31, 0xffff0000, v31
	v_mul_f32_e32 v34, v36, v34
	v_mul_f32_e32 v9, v9, v26
	v_and_b32_e32 v29, 0xffff0000, v29
	v_mul_f32_e32 v8, v8, v34
	v_mul_f32_e32 v26, v9, v9
	v_fmac_f32_e32 v31, v0, v33
	v_fmac_f32_e32 v26, v8, v8
	v_add_f32_e32 v29, v31, v29
	v_mul_f32_e32 v27, v30, v27
	v_fmac_f32_e32 v26, v28, v28
	v_mul_f32_e32 v27, v29, v27
	v_fmac_f32_e32 v26, v27, v27
	s_ashr_i32 s47, s46, 31
	s_lshl_b64 s[6:7], s[46:47], 11
	s_add_u32 s6, s20, s6
	s_addc_u32 s7, s21, s7
	s_nop 1
	v_add_f32_dpp v26, v26, v26 quad_perm:[1,0,3,2] row_mask:0xf bank_mask:0xf
	s_nop 1
	v_add_f32_dpp v26, v26, v26 quad_perm:[2,3,0,1] row_mask:0xf bank_mask:0xf
	s_nop 1
	v_add_f32_dpp v26, v26, v26 row_half_mirror row_mask:0xf bank_mask:0xf
	s_nop 1
	v_add_f32_dpp v26, v26, v26 row_mirror row_mask:0xf bank_mask:0xf
	ds_swizzle_b32 v29, v26 offset:swizzle(SWAP,16)
	s_waitcnt lgkmcnt(0)
	v_add_f32_e32 v26, v26, v29
	v_fmamk_f32 v26, v26, 0x3c000000, v244
	v_rsq_f32_e32 v26, v26
	s_nop 0
	v_mul_f32_e32 v8, v8, v26
	v_mul_f32_e32 v9, v9, v26
	s_waitcnt vmcnt(0)
	v_mul_f32_e32 v8, v2, v8
	v_mul_f32_e32 v9, v3, v9
	v_cvt_pk_bf16_f32 v8, v8, v9
	v_mul_f32_e32 v9, v28, v26
	v_mul_f32_e32 v26, v27, v26
	v_mul_f32_e32 v9, v4, v9
	v_mul_f32_e32 v26, v5, v26
	v_cvt_pk_bf16_f32 v9, v9, v26
	v_lshl_add_u64 v[26:27], v[6:7], 1, s[6:7]
	v_add_co_u32_e32 v26, vcc, 0x16200000, v26
	s_nop 1
	v_addc_co_u32_e32 v27, vcc, 0, v27, vcc
	global_store_dwordx2 v[26:27], v[8:9], off offset:512
	s_and_b64 vcc, exec, s[4:5]
	s_cbranch_vccnz .LBB0_896
	s_branch .LBB0_945

.LBB0_945:
	s_waitcnt vmcnt(5)
	v_and_b32_e32 v9, 0xffff0000, v24
	s_waitcnt vmcnt(2)
	v_lshlrev_b32_e32 v28, 16, v20
	v_and_b32_e32 v20, 0xffff0000, v20
	v_lshlrev_b32_e32 v26, 16, v22
	v_and_b32_e32 v22, 0xffff0000, v22
	v_lshlrev_b32_e32 v30, 16, v18
	v_and_b32_e32 v18, 0xffff0000, v18
	s_waitcnt vmcnt(1)
	v_fmac_f32_e32 v20, v0, v9
	v_add_f32_e32 v9, v20, v18
	v_mul_f32_e32 v18, 0xbfb8aa3b, v22
	v_exp_f32_e32 v18, v18
	v_lshlrev_b32_e32 v8, 16, v24
	v_fmac_f32_e32 v28, v0, v8
	v_lshlrev_b32_e32 v24, 16, v25
	v_add_f32_e32 v18, 1.0, v18
	v_rcp_f32_e32 v18, v18
	v_and_b32_e32 v25, 0xffff0000, v25
	v_lshlrev_b32_e32 v27, 16, v23
	v_lshlrev_b32_e32 v29, 16, v21
	v_and_b32_e32 v21, 0xffff0000, v21
	v_add_f32_e32 v8, v28, v30
	v_mul_f32_e32 v28, 0xbfb8aa3b, v26
	v_and_b32_e32 v23, 0xffff0000, v23
	v_lshlrev_b32_e32 v31, 16, v19
	v_and_b32_e32 v19, 0xffff0000, v19
	v_exp_f32_e32 v28, v28
	v_mul_f32_e32 v18, v18, v22
	v_mul_f32_e32 v22, 0xbfb8aa3b, v27
	v_fmac_f32_e32 v21, v0, v25
	v_exp_f32_e32 v22, v22
	v_add_f32_e32 v19, v21, v19
	v_mul_f32_e32 v21, 0xbfb8aa3b, v23
	v_exp_f32_e32 v21, v21
	v_add_f32_e32 v28, 1.0, v28
	v_rcp_f32_e32 v28, v28
	v_add_f32_e32 v22, 1.0, v22
	v_rcp_f32_e32 v22, v22
	v_add_f32_e32 v21, 1.0, v21
	v_rcp_f32_e32 v21, v21
	v_mul_f32_e32 v26, v28, v26
	v_mul_f32_e32 v9, v9, v18
	v_fmac_f32_e32 v29, v0, v24
	v_mul_f32_e32 v8, v8, v26
	v_mul_f32_e32 v18, v9, v9
	v_add_f32_e32 v20, v29, v31
	v_mul_f32_e32 v22, v22, v27
	v_fmac_f32_e32 v18, v8, v8
	v_mul_f32_e32 v20, v20, v22
	v_mul_f32_e32 v21, v21, v23
	v_fmac_f32_e32 v18, v20, v20
	v_mul_f32_e32 v19, v19, v21
	v_fmac_f32_e32 v18, v19, v19
	s_ashr_i32 s45, s44, 31
	s_lshl_b64 s[4:5], s[44:45], 11
	s_add_u32 s4, s20, s4
	s_addc_u32 s5, s21, s5
	s_nop 1
	v_add_f32_dpp v18, v18, v18 quad_perm:[1,0,3,2] row_mask:0xf bank_mask:0xf
	s_nop 1
	v_add_f32_dpp v18, v18, v18 quad_perm:[2,3,0,1] row_mask:0xf bank_mask:0xf
	s_nop 1
	v_add_f32_dpp v18, v18, v18 row_half_mirror row_mask:0xf bank_mask:0xf
	s_nop 1
	v_add_f32_dpp v18, v18, v18 row_mirror row_mask:0xf bank_mask:0xf
	ds_swizzle_b32 v21, v18 offset:swizzle(SWAP,16)
	s_waitcnt lgkmcnt(0)
	v_add_f32_e32 v18, v18, v21
	v_fmamk_f32 v18, v18, 0x3c000000, v244
	v_rsq_f32_e32 v18, v18
	s_nop 0
	v_mul_f32_e32 v8, v8, v18
	v_mul_f32_e32 v9, v9, v18
	s_waitcnt vmcnt(0)
	v_mul_f32_e32 v8, v2, v8
	v_mul_f32_e32 v9, v3, v9
	v_cvt_pk_bf16_f32 v8, v8, v9
	v_mul_f32_e32 v9, v20, v18
	v_mul_f32_e32 v18, v19, v18
	v_mul_f32_e32 v9, v4, v9
	v_mul_f32_e32 v18, v5, v18
	v_cvt_pk_bf16_f32 v9, v9, v18
	v_lshl_add_u64 v[18:19], v[6:7], 1, s[4:5]
	v_add_co_u32_e32 v18, vcc, 0x16200000, v18
	s_nop 1
	v_addc_co_u32_e32 v19, vcc, 0, v19, vcc
	global_store_dwordx2 v[18:19], v[8:9], off offset:512
	s_branch .LBB0_896
.LBB0_946:
	s_waitcnt vmcnt(5)
	v_and_b32_e32 v9, 0xffff0000, v16
	s_waitcnt vmcnt(3)
	v_lshlrev_b32_e32 v20, 16, v14
	v_and_b32_e32 v14, 0xffff0000, v14
	v_lshlrev_b32_e32 v8, 16, v16
	s_waitcnt vmcnt(2)
	v_lshlrev_b32_e32 v18, 16, v10
	v_and_b32_e32 v10, 0xffff0000, v10
	v_lshlrev_b32_e32 v22, 16, v12
	v_and_b32_e32 v12, 0xffff0000, v12
	s_waitcnt vmcnt(1)
	v_fmac_f32_e32 v14, v0, v9
	v_fmac_f32_e32 v20, v0, v8
	v_add_f32_e32 v9, v14, v12
	v_mul_f32_e32 v12, 0xbfb8aa3b, v10
	v_lshlrev_b32_e32 v16, 16, v17
	v_and_b32_e32 v17, 0xffff0000, v17
	v_lshlrev_b32_e32 v19, 16, v11
	v_lshlrev_b32_e32 v21, 16, v15
	v_and_b32_e32 v15, 0xffff0000, v15
	v_add_f32_e32 v8, v20, v22
	v_mul_f32_e32 v20, 0xbfb8aa3b, v18
	v_exp_f32_e32 v12, v12
	v_and_b32_e32 v11, 0xffff0000, v11
	v_lshlrev_b32_e32 v23, 16, v13
	v_and_b32_e32 v13, 0xffff0000, v13
	v_exp_f32_e32 v20, v20
	v_mul_f32_e32 v14, 0xbfb8aa3b, v19
	v_fmac_f32_e32 v15, v0, v17
	v_fmac_f32_e32 v21, v0, v16
	v_exp_f32_e32 v14, v14
	v_add_f32_e32 v0, v15, v13
	v_mul_f32_e32 v13, 0xbfb8aa3b, v11
	v_exp_f32_e32 v13, v13
	v_add_f32_e32 v12, 1.0, v12
	v_add_f32_e32 v20, 1.0, v20
	v_rcp_f32_e32 v12, v12
	v_rcp_f32_e32 v20, v20
	v_add_f32_e32 v14, 1.0, v14
	v_rcp_f32_e32 v14, v14
	v_add_f32_e32 v13, 1.0, v13
	v_rcp_f32_e32 v13, v13
	v_mul_f32_e32 v10, v12, v10
	v_mul_f32_e32 v18, v20, v18
	v_mul_f32_e32 v9, v9, v10
	v_mul_f32_e32 v8, v8, v18
	v_mul_f32_e32 v10, v9, v9
	v_add_f32_e32 v12, v21, v23
	v_mul_f32_e32 v14, v14, v19
	v_fmac_f32_e32 v10, v8, v8
	v_mul_f32_e32 v12, v12, v14
	v_mul_f32_e32 v11, v13, v11
	v_fmac_f32_e32 v10, v12, v12
	v_mul_f32_e32 v0, v0, v11
	v_fmac_f32_e32 v10, v0, v0
	s_ashr_i32 s43, s42, 31
	s_lshl_b64 s[2:3], s[42:43], 11
	s_add_u32 s2, s20, s2
	s_addc_u32 s3, s21, s3
	s_nop 1
	v_add_f32_dpp v10, v10, v10 quad_perm:[1,0,3,2] row_mask:0xf bank_mask:0xf
	s_nop 1
	v_add_f32_dpp v10, v10, v10 quad_perm:[2,3,0,1] row_mask:0xf bank_mask:0xf
	s_nop 1
	v_add_f32_dpp v10, v10, v10 row_half_mirror row_mask:0xf bank_mask:0xf
	s_nop 1
	v_add_f32_dpp v10, v10, v10 row_mirror row_mask:0xf bank_mask:0xf
	ds_swizzle_b32 v11, v10 offset:swizzle(SWAP,16)
	s_waitcnt lgkmcnt(0)
	v_add_f32_e32 v10, v10, v11
	v_fmamk_f32 v10, v10, 0x3c000000, v244
	v_rsq_f32_e32 v10, v10
	s_nop 0
	v_mul_f32_e32 v8, v8, v10
	s_waitcnt vmcnt(0)
	v_mul_f32_e32 v2, v2, v8
	v_mul_f32_e32 v8, v9, v10
	v_mul_f32_e32 v3, v3, v8
	v_cvt_pk_bf16_f32 v2, v2, v3
	v_mul_f32_e32 v3, v12, v10
	v_mul_f32_e32 v0, v0, v10
	v_mul_f32_e32 v3, v4, v3
	v_mul_f32_e32 v0, v5, v0
	v_lshl_add_u64 v[4:5], v[6:7], 1, s[2:3]
	v_add_co_u32_e32 v4, vcc, 0x16200000, v4
	v_cvt_pk_bf16_f32 v3, v3, v0
	s_nop 1
	v_addc_co_u32_e32 v5, vcc, 0, v5, vcc
	global_store_dwordx2 v[4:5], v[2:3], off offset:512
	s_branch .LBB0_897
